# peeled first K-tile: its two waits count the previous epilogue's stores as still in flight (vmcnt 8+S) for every unit after the first, so the K-loop no longer drains the epilogue stores before startin
# speedup vs baseline: 1.0026x; 1.0016x over previous
; #define PG8_STAGE(bufoff, gbase, voff, p64) do { _Pragma("unroll") for (int _i = 0; _i < 2; ++_i) { \
;         const char* _gb = (const char*)(gbase) + (size_t)_i * (p64); const unsigned _la = ldsbase + (unsigned)(bufoff) + (unsigned)_i * 8192u; \
;         asm volatile("s_mov_b32 m0, %0\n\ts_nop 0\n\tglobal_load_lds_dwordx4 %1, %2" :: "s"(_la), "v"(voff), "s"(_gb) : "memory"); } } while (0)
; #define PG8_LDA(dst, b, h) do { _Pragma("unroll") for (int m = 0; m < 4; ++m) _Pragma("unroll") for (int k = 0; k < 2; ++k) dst[m][k] = *(const LAS bf16x8*)(lds + PG8_SA(b, h) + aoff + m * 2048 + k * 1024); } while (0)
; #define PG8_LDB(dst, b, h) do { _Pragma("unroll") for (int n = 0; n < 2; ++n) _Pragma("unroll") for (int k = 0; k < 2; ++k) dst[n][k] = *(const LAS bf16x8*)(lds + PG8_SB(b, h) + boff + n * 2048 + k * 1024); } while (0)
; #define PG8_MMA(ai, bj, At, Bt) do { __builtin_amdgcn_s_setprio(1); _Pragma("unroll") for (int m = 0; m < 4; ++m) _Pragma("unroll") for (int n = 0; n < 2; ++n) _Pragma("unroll") for (int k = 0; k < 2; ++k) \
;         acc[ai][bj][m][n] = __builtin_amdgcn_mfma_f32_16x16x32_bf16(Bt[n][k], At[m][k], acc[ai][bj][m][n], 0, 0, 0); __builtin_amdgcn_s_setprio(0); } while (0)
; #define PG8_WAIT_V(n) asm volatile("s_waitcnt vmcnt(" #n ")" ::: "memory")
; #define PG8_WAIT_L(n) asm volatile("s_waitcnt lgkmcnt(" #n ")" ::: "memory")
; #define PG8_BAR __builtin_amdgcn_s_barrier()
; #define PG8_SCHED __builtin_amdgcn_sched_barrier(0)
; template <class Epi, class Sched>
; __device__ __forceinline__ void gemm_phase(LAS unsigned char* lds, const Sched& S, const Epi& E) {
;     ...
;             PG8_LDB(B0, 0, 0); PG8_LDB(B1, 0, 1); PG8_SCHED; PG8_LDA(At, 0, 0); PG8_STAGE(PG8_SA(1, 1), a1 + hA, voffA, hA / 2);
;             PG8_WAIT_V(8); PG8_WAIT_L(0); PG8_BAR; PG8_MMA(0, 0, At, B0); PG8_MMA(0, 1, At, B1); PG8_BAR; PG8_SCHED;
;             PG8_LDA(At, 0, 1); PG8_STAGE(PG8_SB(0, 0), b2, vB2, hB2 / 2); PG8_STAGE(PG8_SB(0, 1), b2 + hB2, vB2, hB2 / 2); PG8_STAGE(PG8_SA(0, 0), a2, vA2, hA2 / 2);
.LBB0_303:
	s_add_u32 s38, s38, 0x40080
	s_addc_u32 s39, s39, 0
	s_add_u32 s62, s40, 0x100
	s_addc_u32 s63, s41, 0
	s_mov_b32 s64, -2
	ds_read_b128 v[144:147], v138
	ds_read_b128 v[148:151], v138 offset:1024
	ds_read_b128 v[152:155], v138 offset:2048
	ds_read_b128 v[156:159], v138 offset:3072
	ds_read_b128 v[160:163], v139
	ds_read_b128 v[164:167], v139 offset:1024
	ds_read_b128 v[168:171], v139 offset:2048
	ds_read_b128 v[172:175], v139 offset:3072
	s_add_u32 s30, s38, 0xfffc0080
	s_addc_u32 s31, s39, -1
	s_cmp_eq_u32 s64, 12
	s_cselect_b32 s40, s24, s30
	s_cselect_b32 s41, s25, s31
	s_cselect_b32 s44, s26, s62
	s_cselect_b32 s45, s27, s63
	s_add_u32 s42, s40, 0x80
	s_addc_u32 s43, s41, 0
	ds_read_b128 v[178:181], v140
	ds_read_b128 v[182:185], v140 offset:1024
	ds_read_b128 v[186:189], v140 offset:2048
	ds_read_b128 v[190:193], v140 offset:3072
	ds_read_b128 v[194:197], v140 offset:4096
	ds_read_b128 v[198:201], v140 offset:5120
	ds_read_b128 v[202:205], v140 offset:6144
	ds_read_b128 v[206:209], v140 offset:7168
	s_mov_b32 m0, s55
	s_nop 0
	global_load_lds_dwordx4 v134, s[38:39]
	s_add_u32 s66, s38, 0x20000
	s_mov_b32 m0, s56
	s_addc_u32 s67, s39, 0
	global_load_lds_dwordx4 v134, s[66:67]
	s_cmp_eq_u32 s23, 0
	s_cbranch_scc1 .Lpeel_strict_5680_1
	s_waitcnt vmcnt(16) lgkmcnt(0)
	s_branch .Lpeel_join_5680_1
.Lpeel_strict_5680_1:
	s_waitcnt vmcnt(8) lgkmcnt(0)
.Lpeel_join_5680_1:
	s_barrier
	v_mfma_f32_16x16x32_bf16 v[124:127], v[144:147], v[178:181], 0
	v_mfma_f32_16x16x32_bf16 v[120:123], v[152:155], v[178:181], 0
	v_mfma_f32_16x16x32_bf16 v[108:111], v[144:147], v[186:189], 0
	v_mfma_f32_16x16x32_bf16 v[104:107], v[152:155], v[186:189], 0
	v_mfma_f32_16x16x32_bf16 v[92:95], v[144:147], v[194:197], 0
	v_mfma_f32_16x16x32_bf16 v[88:91], v[152:155], v[194:197], 0
	v_mfma_f32_16x16x32_bf16 v[76:79], v[144:147], v[202:205], 0
	v_mfma_f32_16x16x32_bf16 v[72:75], v[152:155], v[202:205], 0
	v_mfma_f32_16x16x32_bf16 v[124:127], v[148:151], v[182:185], v[124:127]
	v_mfma_f32_16x16x32_bf16 v[120:123], v[156:159], v[182:185], v[120:123]
	v_mfma_f32_16x16x32_bf16 v[108:111], v[148:151], v[190:193], v[108:111]
	v_mfma_f32_16x16x32_bf16 v[104:107], v[156:159], v[190:193], v[104:107]
	v_mfma_f32_16x16x32_bf16 v[92:95], v[148:151], v[198:201], v[92:95]
	v_mfma_f32_16x16x32_bf16 v[88:91], v[156:159], v[198:201], v[88:91]
	v_mfma_f32_16x16x32_bf16 v[76:79], v[148:151], v[206:209], v[76:79]
	v_mfma_f32_16x16x32_bf16 v[72:75], v[156:159], v[206:209], v[72:75]
	v_mfma_f32_16x16x32_bf16 v[116:119], v[160:163], v[178:181], 0
	v_mfma_f32_16x16x32_bf16 v[112:115], v[168:171], v[178:181], 0
	v_mfma_f32_16x16x32_bf16 v[100:103], v[160:163], v[186:189], 0
	v_mfma_f32_16x16x32_bf16 v[96:99], v[168:171], v[186:189], 0
	v_mfma_f32_16x16x32_bf16 v[84:87], v[160:163], v[194:197], 0
	v_mfma_f32_16x16x32_bf16 v[80:83], v[168:171], v[194:197], 0
	v_mfma_f32_16x16x32_bf16 v[68:71], v[160:163], v[202:205], 0
	v_mfma_f32_16x16x32_bf16 v[64:67], v[168:171], v[202:205], 0
	v_mfma_f32_16x16x32_bf16 v[116:119], v[164:167], v[182:185], v[116:119]
	v_mfma_f32_16x16x32_bf16 v[112:115], v[172:175], v[182:185], v[112:115]
	v_mfma_f32_16x16x32_bf16 v[100:103], v[164:167], v[190:193], v[100:103]
	v_mfma_f32_16x16x32_bf16 v[96:99], v[172:175], v[190:193], v[96:99]
	v_mfma_f32_16x16x32_bf16 v[84:87], v[164:167], v[198:201], v[84:87]
	v_mfma_f32_16x16x32_bf16 v[80:83], v[172:175], v[198:201], v[80:83]
	v_mfma_f32_16x16x32_bf16 v[68:71], v[164:167], v[206:209], v[68:71]
	v_mfma_f32_16x16x32_bf16 v[64:67], v[172:175], v[206:209], v[64:67]
	s_add_i32 s64, s64, 2
	s_add_u32 s38, s38, 0x100
	s_addc_u32 s39, s39, 0
	s_add_u32 s62, s62, 0x100
	s_addc_u32 s63, s63, 0
	s_barrier
	s_add_u32 s66, s44, 0x20000
	ds_read_b128 v[178:181], v140 offset:16384
	ds_read_b128 v[182:185], v140 offset:17408
	ds_read_b128 v[186:189], v140 offset:18432
	ds_read_b128 v[190:193], v140 offset:19456
	ds_read_b128 v[194:197], v140 offset:20480
	ds_read_b128 v[198:201], v140 offset:21504
	ds_read_b128 v[202:205], v140 offset:22528
	ds_read_b128 v[206:209], v140 offset:23552
	s_mov_b32 m0, s33
	s_nop 0
	global_load_lds_dwordx4 v135, s[44:45]
	s_mov_b32 m0, s34
	s_addc_u32 s67, s45, 0
	global_load_lds_dwordx4 v135, s[66:67]
	s_add_u32 s66, s44, 0x40000
	s_mov_b32 m0, s35
	s_addc_u32 s67, s45, 0
	global_load_lds_dwordx4 v135, s[66:67]
	s_add_u32 s66, s44, 0x60000
	s_mov_b32 m0, s36
	s_addc_u32 s67, s45, 0
	global_load_lds_dwordx4 v135, s[66:67]
	s_mov_b32 m0, s12
	s_nop 0
	global_load_lds_dwordx4 v134, s[40:41]
	s_add_u32 s66, s40, 0x20000
	s_mov_b32 m0, s37
	s_addc_u32 s67, s41, 0
	global_load_lds_dwordx4 v134, s[66:67]
	s_cmp_eq_u32 s23, 0
	s_cbranch_scc1 .Lpeel_strict_5680_0
	s_waitcnt vmcnt(16) lgkmcnt(0)
	s_branch .Lpeel_join_5680_0

; #define PG8_MMA(ai, bj, At, Bt) do { __builtin_amdgcn_s_setprio(1); _Pragma("unroll") for (int m = 0; m < 4; ++m) _Pragma("unroll") for (int n = 0; n < 2; ++n) _Pragma("unroll") for (int k = 0; k < 2; ++k) \
;         acc[ai][bj][m][n] = __builtin_amdgcn_mfma_f32_16x16x32_bf16(Bt[n][k], At[m][k], acc[ai][bj][m][n], 0, 0, 0); __builtin_amdgcn_s_setprio(0); } while (0)
; #define PG8_WAIT_V(n) asm volatile("s_waitcnt vmcnt(" #n ")" ::: "memory")
; #define PG8_WAIT_L(n) asm volatile("s_waitcnt lgkmcnt(" #n ")" ::: "memory")
; #define PG8_BAR __builtin_amdgcn_s_barrier()
; #define PG8_SCHED __builtin_amdgcn_sched_barrier(0)
; template <class Epi, class Sched>
; __device__ __forceinline__ void gemm_phase(LAS unsigned char* lds, const Sched& S, const Epi& E) {
;     ...
;             PG8_WAIT_V(8); PG8_WAIT_L(0); PG8_BAR; PG8_MMA(1, 0, At, B0); PG8_MMA(1, 1, At, B1); PG8_BAR; PG8_SCHED;
.Lpeel_join_5680_0:
	s_barrier
	v_mfma_f32_16x16x32_bf16 v[60:63], v[144:147], v[178:181], 0
	v_mfma_f32_16x16x32_bf16 v[56:59], v[152:155], v[178:181], 0
	v_mfma_f32_16x16x32_bf16 v[44:47], v[144:147], v[186:189], 0
	v_mfma_f32_16x16x32_bf16 v[40:43], v[152:155], v[186:189], 0
	v_mfma_f32_16x16x32_bf16 v[28:31], v[144:147], v[194:197], 0
	v_mfma_f32_16x16x32_bf16 v[24:27], v[152:155], v[194:197], 0
	v_mfma_f32_16x16x32_bf16 v[12:15], v[144:147], v[202:205], 0
	v_mfma_f32_16x16x32_bf16 v[8:11], v[152:155], v[202:205], 0
	v_mfma_f32_16x16x32_bf16 v[60:63], v[148:151], v[182:185], v[60:63]
	v_mfma_f32_16x16x32_bf16 v[56:59], v[156:159], v[182:185], v[56:59]
	v_mfma_f32_16x16x32_bf16 v[44:47], v[148:151], v[190:193], v[44:47]
	v_mfma_f32_16x16x32_bf16 v[40:43], v[156:159], v[190:193], v[40:43]
	v_mfma_f32_16x16x32_bf16 v[28:31], v[148:151], v[198:201], v[28:31]
	v_mfma_f32_16x16x32_bf16 v[24:27], v[156:159], v[198:201], v[24:27]
	v_mfma_f32_16x16x32_bf16 v[12:15], v[148:151], v[206:209], v[12:15]
	v_mfma_f32_16x16x32_bf16 v[8:11], v[156:159], v[206:209], v[8:11]
	v_mfma_f32_16x16x32_bf16 v[52:55], v[160:163], v[178:181], 0
	v_mfma_f32_16x16x32_bf16 v[48:51], v[168:171], v[178:181], 0
	v_mfma_f32_16x16x32_bf16 v[36:39], v[160:163], v[186:189], 0
	v_mfma_f32_16x16x32_bf16 v[32:35], v[168:171], v[186:189], 0
	v_mfma_f32_16x16x32_bf16 v[20:23], v[160:163], v[194:197], 0
	v_mfma_f32_16x16x32_bf16 v[16:19], v[168:171], v[194:197], 0
	v_mfma_f32_16x16x32_bf16 v[4:7], v[160:163], v[202:205], 0
	v_mfma_f32_16x16x32_bf16 v[0:3], v[168:171], v[202:205], 0
	v_mfma_f32_16x16x32_bf16 v[52:55], v[164:167], v[182:185], v[52:55]
	v_mfma_f32_16x16x32_bf16 v[48:51], v[172:175], v[182:185], v[48:51]
	v_mfma_f32_16x16x32_bf16 v[36:39], v[164:167], v[190:193], v[36:39]
	v_mfma_f32_16x16x32_bf16 v[32:35], v[172:175], v[190:193], v[32:35]
	v_mfma_f32_16x16x32_bf16 v[20:23], v[164:167], v[198:201], v[20:23]
	v_mfma_f32_16x16x32_bf16 v[16:19], v[172:175], v[198:201], v[16:19]
	v_mfma_f32_16x16x32_bf16 v[4:7], v[164:167], v[206:209], v[4:7]
	v_mfma_f32_16x16x32_bf16 v[0:3], v[172:175], v[206:209], v[0:3]
	s_barrier
	s_branch .Lpeel_mid_5680

; #define PG8_STAGE(bufoff, gbase, voff, p64) do { _Pragma("unroll") for (int _i = 0; _i < 2; ++_i) { \
;         const char* _gb = (const char*)(gbase) + (size_t)_i * (p64); const unsigned _la = ldsbase + (unsigned)(bufoff) + (unsigned)_i * 8192u; \
;         asm volatile("s_mov_b32 m0, %0\n\ts_nop 0\n\tglobal_load_lds_dwordx4 %1, %2" :: "s"(_la), "v"(voff), "s"(_gb) : "memory"); } } while (0)
; #define PG8_LDA(dst, b, h) do { _Pragma("unroll") for (int m = 0; m < 4; ++m) _Pragma("unroll") for (int k = 0; k < 2; ++k) dst[m][k] = *(const LAS bf16x8*)(lds + PG8_SA(b, h) + aoff + m * 2048 + k * 1024); } while (0)
; #define PG8_LDB(dst, b, h) do { _Pragma("unroll") for (int n = 0; n < 2; ++n) _Pragma("unroll") for (int k = 0; k < 2; ++k) dst[n][k] = *(const LAS bf16x8*)(lds + PG8_SB(b, h) + boff + n * 2048 + k * 1024); } while (0)
; #define PG8_MMA(ai, bj, At, Bt) do { __builtin_amdgcn_s_setprio(1); _Pragma("unroll") for (int m = 0; m < 4; ++m) _Pragma("unroll") for (int n = 0; n < 2; ++n) _Pragma("unroll") for (int k = 0; k < 2; ++k) \
;         acc[ai][bj][m][n] = __builtin_amdgcn_mfma_f32_16x16x32_bf16(Bt[n][k], At[m][k], acc[ai][bj][m][n], 0, 0, 0); __builtin_amdgcn_s_setprio(0); } while (0)
; #define PG8_WAIT_V(n) asm volatile("s_waitcnt vmcnt(" #n ")" ::: "memory")
; #define PG8_WAIT_L(n) asm volatile("s_waitcnt lgkmcnt(" #n ")" ::: "memory")
; #define PG8_BAR __builtin_amdgcn_s_barrier()
; #define PG8_SCHED __builtin_amdgcn_sched_barrier(0)
; template <class Epi, class Sched>
; __device__ __forceinline__ void gemm_phase(LAS unsigned char* lds, const Sched& S, const Epi& E) {
;     ...
;             PG8_LDB(B0, 0, 0); PG8_LDB(B1, 0, 1); PG8_SCHED; PG8_LDA(At, 0, 0); PG8_STAGE(PG8_SA(1, 1), a1 + hA, voffA, hA / 2);
;             PG8_WAIT_V(8); PG8_WAIT_L(0); PG8_BAR; PG8_MMA(0, 0, At, B0); PG8_MMA(0, 1, At, B1); PG8_BAR; PG8_SCHED;
.LBB0_980:
	s_add_u32 s26, s26, 0x40080
	s_addc_u32 s27, s27, 0
	s_add_u32 s62, s38, 0x100
	s_addc_u32 s63, s39, 0
	s_mov_b32 s65, -2
	s_waitcnt vmcnt(3)
	s_waitcnt vmcnt(2)
	s_waitcnt vmcnt(1)
	s_waitcnt vmcnt(0)
	ds_read_b128 v[112:115], v162
	ds_read_b128 v[116:119], v162 offset:1024
	ds_read_b128 v[140:143], v162 offset:2048
	ds_read_b128 v[144:147], v162 offset:3072
	ds_read_b128 v[148:151], v163
	ds_read_b128 v[152:155], v163 offset:1024
	ds_read_b128 v[168:171], v163 offset:2048
	ds_read_b128 v[172:175], v163 offset:3072
	s_add_u32 s30, s26, 0xfffc0080
	s_addc_u32 s38, s27, -1
	s_cmp_eq_u32 s65, 12
	s_cselect_b32 s39, s23, s38
	s_cselect_b32 s38, s22, s30
	s_cselect_b32 s42, s24, s62
	s_cselect_b32 s43, s25, s63
	s_add_u32 s40, s38, 0x80
	s_addc_u32 s41, s39, 0
	ds_read_b128 v[178:181], v164
	ds_read_b128 v[182:185], v164 offset:1024
	ds_read_b128 v[186:189], v164 offset:2048
	ds_read_b128 v[190:193], v164 offset:3072
	ds_read_b128 v[194:197], v164 offset:4096
	ds_read_b128 v[198:201], v164 offset:5120
	ds_read_b128 v[202:205], v164 offset:6144
	ds_read_b128 v[206:209], v164 offset:7168
	s_mov_b32 m0, s58
	s_nop 0
	global_load_lds_dwordx4 v158, s[26:27]
	s_add_u32 s66, s26, 0x20000
	s_mov_b32 m0, s59
	s_addc_u32 s67, s27, 0
	global_load_lds_dwordx4 v158, s[66:67]
	s_cmp_eq_u32 s21, 0
	s_cbranch_scc1 .Lpeel_strict_28618_1
	s_waitcnt vmcnt(24) lgkmcnt(0)
	s_branch .Lpeel_join_28618_1

; #define PG8_STAGE(bufoff, gbase, voff, p64) do { _Pragma("unroll") for (int _i = 0; _i < 2; ++_i) { \
;         const char* _gb = (const char*)(gbase) + (size_t)_i * (p64); const unsigned _la = ldsbase + (unsigned)(bufoff) + (unsigned)_i * 8192u; \
;         asm volatile("s_mov_b32 m0, %0\n\ts_nop 0\n\tglobal_load_lds_dwordx4 %1, %2" :: "s"(_la), "v"(voff), "s"(_gb) : "memory"); } } while (0)
; #define PG8_LDA(dst, b, h) do { _Pragma("unroll") for (int m = 0; m < 4; ++m) _Pragma("unroll") for (int k = 0; k < 2; ++k) dst[m][k] = *(const LAS bf16x8*)(lds + PG8_SA(b, h) + aoff + m * 2048 + k * 1024); } while (0)
; #define PG8_MMA(ai, bj, At, Bt) do { __builtin_amdgcn_s_setprio(1); _Pragma("unroll") for (int m = 0; m < 4; ++m) _Pragma("unroll") for (int n = 0; n < 2; ++n) _Pragma("unroll") for (int k = 0; k < 2; ++k) \
;         acc[ai][bj][m][n] = __builtin_amdgcn_mfma_f32_16x16x32_bf16(Bt[n][k], At[m][k], acc[ai][bj][m][n], 0, 0, 0); __builtin_amdgcn_s_setprio(0); } while (0)
; #define PG8_WAIT_V(n) asm volatile("s_waitcnt vmcnt(" #n ")" ::: "memory")
; #define PG8_WAIT_L(n) asm volatile("s_waitcnt lgkmcnt(" #n ")" ::: "memory")
; #define PG8_BAR __builtin_amdgcn_s_barrier()
; #define PG8_SCHED __builtin_amdgcn_sched_barrier(0)
; template <class Epi, class Sched>
; __device__ __forceinline__ void gemm_phase(LAS unsigned char* lds, const Sched& S, const Epi& E) {
;     ...
;             PG8_WAIT_V(8); PG8_WAIT_L(0); PG8_BAR; PG8_MMA(0, 0, At, B0); PG8_MMA(0, 1, At, B1); PG8_BAR; PG8_SCHED;
;             PG8_LDA(At, 0, 1); PG8_STAGE(PG8_SB(0, 0), b2, vB2, hB2 / 2); PG8_STAGE(PG8_SB(0, 1), b2 + hB2, vB2, hB2 / 2); PG8_STAGE(PG8_SA(0, 0), a2, vA2, hA2 / 2);
.Lpeel_join_28618_1:
	s_barrier
	v_mfma_f32_16x16x32_bf16 v[132:135], v[112:115], v[178:181], 0
	v_mfma_f32_16x16x32_bf16 v[128:131], v[140:143], v[178:181], 0
	v_mfma_f32_16x16x32_bf16 v[124:127], v[112:115], v[186:189], 0
	v_mfma_f32_16x16x32_bf16 v[120:123], v[140:143], v[186:189], 0
	v_mfma_f32_16x16x32_bf16 v[108:111], v[112:115], v[194:197], 0
	v_mfma_f32_16x16x32_bf16 v[104:107], v[140:143], v[194:197], 0
	v_mfma_f32_16x16x32_bf16 v[100:103], v[112:115], v[202:205], 0
	v_mfma_f32_16x16x32_bf16 v[96:99], v[140:143], v[202:205], 0
	v_mfma_f32_16x16x32_bf16 v[132:135], v[116:119], v[182:185], v[132:135]
	v_mfma_f32_16x16x32_bf16 v[128:131], v[144:147], v[182:185], v[128:131]
	v_mfma_f32_16x16x32_bf16 v[124:127], v[116:119], v[190:193], v[124:127]
	v_mfma_f32_16x16x32_bf16 v[120:123], v[144:147], v[190:193], v[120:123]
	v_mfma_f32_16x16x32_bf16 v[108:111], v[116:119], v[198:201], v[108:111]
	v_mfma_f32_16x16x32_bf16 v[104:107], v[144:147], v[198:201], v[104:107]
	v_mfma_f32_16x16x32_bf16 v[100:103], v[116:119], v[206:209], v[100:103]
	v_mfma_f32_16x16x32_bf16 v[96:99], v[144:147], v[206:209], v[96:99]
	v_mfma_f32_16x16x32_bf16 v[60:63], v[148:151], v[178:181], 0
	v_mfma_f32_16x16x32_bf16 v[56:59], v[168:171], v[178:181], 0
	v_mfma_f32_16x16x32_bf16 v[52:55], v[148:151], v[186:189], 0
	v_mfma_f32_16x16x32_bf16 v[48:51], v[168:171], v[186:189], 0
	v_mfma_f32_16x16x32_bf16 v[44:47], v[148:151], v[194:197], 0
	v_mfma_f32_16x16x32_bf16 v[40:43], v[168:171], v[194:197], 0
	v_mfma_f32_16x16x32_bf16 v[36:39], v[148:151], v[202:205], 0
	v_mfma_f32_16x16x32_bf16 v[32:35], v[168:171], v[202:205], 0
	v_mfma_f32_16x16x32_bf16 v[60:63], v[152:155], v[182:185], v[60:63]
	v_mfma_f32_16x16x32_bf16 v[56:59], v[172:175], v[182:185], v[56:59]
	v_mfma_f32_16x16x32_bf16 v[52:55], v[152:155], v[190:193], v[52:55]
	v_mfma_f32_16x16x32_bf16 v[48:51], v[172:175], v[190:193], v[48:51]
	v_mfma_f32_16x16x32_bf16 v[44:47], v[152:155], v[198:201], v[44:47]
	v_mfma_f32_16x16x32_bf16 v[40:43], v[172:175], v[198:201], v[40:43]
	v_mfma_f32_16x16x32_bf16 v[36:39], v[152:155], v[206:209], v[36:39]
	v_mfma_f32_16x16x32_bf16 v[32:35], v[172:175], v[206:209], v[32:35]
	s_add_i32 s65, s65, 2
	s_add_u32 s26, s26, 0x100
	s_addc_u32 s27, s27, 0
	s_add_u32 s62, s62, 0x100
	s_addc_u32 s63, s63, 0
	s_barrier
	s_add_u32 s66, s42, 0x20000
	ds_read_b128 v[178:181], v164 offset:16384
	ds_read_b128 v[182:185], v164 offset:17408
	ds_read_b128 v[186:189], v164 offset:18432
	ds_read_b128 v[190:193], v164 offset:19456
	ds_read_b128 v[194:197], v164 offset:20480
	ds_read_b128 v[198:201], v164 offset:21504
	ds_read_b128 v[202:205], v164 offset:22528
	ds_read_b128 v[206:209], v164 offset:23552
	s_mov_b32 m0, s35
	s_nop 0
	global_load_lds_dwordx4 v159, s[42:43]
	s_mov_b32 m0, s36
	s_addc_u32 s67, s43, 0
	global_load_lds_dwordx4 v159, s[66:67]
	s_add_u32 s66, s42, 0x40000
	s_mov_b32 m0, s37
	s_addc_u32 s67, s43, 0
	global_load_lds_dwordx4 v159, s[66:67]
	s_add_u32 s66, s42, 0x60000
	s_mov_b32 m0, s44
	s_addc_u32 s67, s43, 0
	global_load_lds_dwordx4 v159, s[66:67]
	s_mov_b32 m0, s34
	s_nop 0
	global_load_lds_dwordx4 v158, s[38:39]
	s_add_u32 s66, s38, 0x20000
	s_mov_b32 m0, s45
	s_addc_u32 s67, s39, 0
	global_load_lds_dwordx4 v158, s[66:67]
	s_cmp_eq_u32 s21, 0
	s_cbranch_scc1 .Lpeel_strict_28618_0
	s_waitcnt vmcnt(24) lgkmcnt(0)
	s_branch .Lpeel_join_28618_0

; #define PG8_MMA(ai, bj, At, Bt) do { __builtin_amdgcn_s_setprio(1); _Pragma("unroll") for (int m = 0; m < 4; ++m) _Pragma("unroll") for (int n = 0; n < 2; ++n) _Pragma("unroll") for (int k = 0; k < 2; ++k) \
;         acc[ai][bj][m][n] = __builtin_amdgcn_mfma_f32_16x16x32_bf16(Bt[n][k], At[m][k], acc[ai][bj][m][n], 0, 0, 0); __builtin_amdgcn_s_setprio(0); } while (0)
; #define PG8_WAIT_V(n) asm volatile("s_waitcnt vmcnt(" #n ")" ::: "memory")
; #define PG8_WAIT_L(n) asm volatile("s_waitcnt lgkmcnt(" #n ")" ::: "memory")
; #define PG8_BAR __builtin_amdgcn_s_barrier()
; #define PG8_SCHED __builtin_amdgcn_sched_barrier(0)
; template <class Epi, class Sched>
; __device__ __forceinline__ void gemm_phase(LAS unsigned char* lds, const Sched& S, const Epi& E) {
;     ...
;             PG8_WAIT_V(8); PG8_WAIT_L(0); PG8_BAR; PG8_MMA(1, 0, At, B0); PG8_MMA(1, 1, At, B1); PG8_BAR; PG8_SCHED;
.Lpeel_join_28618_0:
	s_barrier
	v_mfma_f32_16x16x32_bf16 v[92:95], v[112:115], v[178:181], 0
	v_mfma_f32_16x16x32_bf16 v[88:91], v[140:143], v[178:181], 0
	v_mfma_f32_16x16x32_bf16 v[84:87], v[112:115], v[186:189], 0
	v_mfma_f32_16x16x32_bf16 v[80:83], v[140:143], v[186:189], 0
	v_mfma_f32_16x16x32_bf16 v[76:79], v[112:115], v[194:197], 0
	v_mfma_f32_16x16x32_bf16 v[72:75], v[140:143], v[194:197], 0
	v_mfma_f32_16x16x32_bf16 v[68:71], v[112:115], v[202:205], 0
	v_mfma_f32_16x16x32_bf16 v[64:67], v[140:143], v[202:205], 0
	v_mfma_f32_16x16x32_bf16 v[92:95], v[116:119], v[182:185], v[92:95]
	v_mfma_f32_16x16x32_bf16 v[88:91], v[144:147], v[182:185], v[88:91]
	v_mfma_f32_16x16x32_bf16 v[84:87], v[116:119], v[190:193], v[84:87]
	v_mfma_f32_16x16x32_bf16 v[80:83], v[144:147], v[190:193], v[80:83]
	v_mfma_f32_16x16x32_bf16 v[76:79], v[116:119], v[198:201], v[76:79]
	v_mfma_f32_16x16x32_bf16 v[72:75], v[144:147], v[198:201], v[72:75]
	v_mfma_f32_16x16x32_bf16 v[68:71], v[116:119], v[206:209], v[68:71]
	v_mfma_f32_16x16x32_bf16 v[64:67], v[144:147], v[206:209], v[64:67]
	v_mfma_f32_16x16x32_bf16 v[28:31], v[148:151], v[178:181], 0
	v_mfma_f32_16x16x32_bf16 v[24:27], v[168:171], v[178:181], 0
	v_mfma_f32_16x16x32_bf16 v[20:23], v[148:151], v[186:189], 0
	v_mfma_f32_16x16x32_bf16 v[16:19], v[168:171], v[186:189], 0
	v_mfma_f32_16x16x32_bf16 v[12:15], v[148:151], v[194:197], 0
	v_mfma_f32_16x16x32_bf16 v[8:11], v[168:171], v[194:197], 0
	v_mfma_f32_16x16x32_bf16 v[4:7], v[148:151], v[202:205], 0
	v_mfma_f32_16x16x32_bf16 v[0:3], v[168:171], v[202:205], 0
	v_mfma_f32_16x16x32_bf16 v[28:31], v[152:155], v[182:185], v[28:31]
	v_mfma_f32_16x16x32_bf16 v[24:27], v[172:175], v[182:185], v[24:27]
	v_mfma_f32_16x16x32_bf16 v[20:23], v[152:155], v[190:193], v[20:23]
	v_mfma_f32_16x16x32_bf16 v[16:19], v[172:175], v[190:193], v[16:19]
	v_mfma_f32_16x16x32_bf16 v[12:15], v[152:155], v[198:201], v[12:15]
	v_mfma_f32_16x16x32_bf16 v[8:11], v[172:175], v[198:201], v[8:11]
	v_mfma_f32_16x16x32_bf16 v[4:7], v[152:155], v[206:209], v[4:7]
	v_mfma_f32_16x16x32_bf16 v[0:3], v[172:175], v[206:209], v[0:3]
	s_barrier
	s_branch .Lpeel_mid_28618

; #define PG8_STAGE(bufoff, gbase, voff, p64) do { _Pragma("unroll") for (int _i = 0; _i < 2; ++_i) { \
;         const char* _gb = (const char*)(gbase) + (size_t)_i * (p64); const unsigned _la = ldsbase + (unsigned)(bufoff) + (unsigned)_i * 8192u; \
;         asm volatile("s_mov_b32 m0, %0\n\ts_nop 0\n\tglobal_load_lds_dwordx4 %1, %2" :: "s"(_la), "v"(voff), "s"(_gb) : "memory"); } } while (0)
; #define PG8_LDA(dst, b, h) do { _Pragma("unroll") for (int m = 0; m < 4; ++m) _Pragma("unroll") for (int k = 0; k < 2; ++k) dst[m][k] = *(const LAS bf16x8*)(lds + PG8_SA(b, h) + aoff + m * 2048 + k * 1024); } while (0)
; #define PG8_LDB(dst, b, h) do { _Pragma("unroll") for (int n = 0; n < 2; ++n) _Pragma("unroll") for (int k = 0; k < 2; ++k) dst[n][k] = *(const LAS bf16x8*)(lds + PG8_SB(b, h) + boff + n * 2048 + k * 1024); } while (0)
; #define PG8_MMA(ai, bj, At, Bt) do { __builtin_amdgcn_s_setprio(1); _Pragma("unroll") for (int m = 0; m < 4; ++m) _Pragma("unroll") for (int n = 0; n < 2; ++n) _Pragma("unroll") for (int k = 0; k < 2; ++k) \
;         acc[ai][bj][m][n] = __builtin_amdgcn_mfma_f32_16x16x32_bf16(Bt[n][k], At[m][k], acc[ai][bj][m][n], 0, 0, 0); __builtin_amdgcn_s_setprio(0); } while (0)
; #define PG8_WAIT_V(n) asm volatile("s_waitcnt vmcnt(" #n ")" ::: "memory")
; #define PG8_WAIT_L(n) asm volatile("s_waitcnt lgkmcnt(" #n ")" ::: "memory")
; #define PG8_BAR __builtin_amdgcn_s_barrier()
; #define PG8_SCHED __builtin_amdgcn_sched_barrier(0)
; template <class Epi, class Sched>
; __device__ __forceinline__ void gemm_phase(LAS unsigned char* lds, const Sched& S, const Epi& E) {
;     ...
;             PG8_LDB(B0, 0, 0); PG8_LDB(B1, 0, 1); PG8_SCHED; PG8_LDA(At, 0, 0); PG8_STAGE(PG8_SA(1, 1), a1 + hA, voffA, hA / 2);
;             PG8_WAIT_V(8); PG8_WAIT_L(0); PG8_BAR; PG8_MMA(0, 0, At, B0); PG8_MMA(0, 1, At, B1); PG8_BAR; PG8_SCHED;
.LBB0_1010:
	s_add_u32 s26, s26, 0x40080
	s_addc_u32 s27, s27, 0
	s_add_u32 s61, s38, 0x100
	s_addc_u32 s62, s39, 0
	s_mov_b32 s63, -2
	ds_read_b128 v[144:147], v138
	ds_read_b128 v[148:151], v138 offset:1024
	ds_read_b128 v[152:155], v138 offset:2048
	ds_read_b128 v[156:159], v138 offset:3072
	ds_read_b128 v[160:163], v139
	ds_read_b128 v[164:167], v139 offset:1024
	ds_read_b128 v[168:171], v139 offset:2048
	ds_read_b128 v[172:175], v139 offset:3072
	s_add_u32 s30, s26, 0xfffc0080
	s_addc_u32 s38, s27, -1
	s_cmp_eq_u32 s63, 12
	s_cselect_b32 s39, s23, s38
	s_cselect_b32 s38, s22, s30
	s_cselect_b32 s42, s24, s61
	s_cselect_b32 s43, s25, s62
	s_add_u32 s40, s38, 0x80
	s_addc_u32 s41, s39, 0
	ds_read_b128 v[178:181], v140
	ds_read_b128 v[182:185], v140 offset:1024
	ds_read_b128 v[186:189], v140 offset:2048
	ds_read_b128 v[190:193], v140 offset:3072
	ds_read_b128 v[194:197], v140 offset:4096
	ds_read_b128 v[198:201], v140 offset:5120
	ds_read_b128 v[202:205], v140 offset:6144
	ds_read_b128 v[206:209], v140 offset:7168
	s_mov_b32 m0, s57
	s_nop 0
	global_load_lds_dwordx4 v134, s[26:27]
	s_add_u32 s66, s26, 0x20000
	s_mov_b32 m0, s58
	s_addc_u32 s67, s27, 0
	global_load_lds_dwordx4 v134, s[66:67]
	s_cmp_eq_u32 s21, 0
	s_cbranch_scc1 .Lpeel_strict_30522_1
	s_waitcnt vmcnt(16) lgkmcnt(0)
	s_branch .Lpeel_join_30522_1

; #define PG8_STAGE(bufoff, gbase, voff, p64) do { _Pragma("unroll") for (int _i = 0; _i < 2; ++_i) { \
;         const char* _gb = (const char*)(gbase) + (size_t)_i * (p64); const unsigned _la = ldsbase + (unsigned)(bufoff) + (unsigned)_i * 8192u; \
;         asm volatile("s_mov_b32 m0, %0\n\ts_nop 0\n\tglobal_load_lds_dwordx4 %1, %2" :: "s"(_la), "v"(voff), "s"(_gb) : "memory"); } } while (0)
; #define PG8_LDA(dst, b, h) do { _Pragma("unroll") for (int m = 0; m < 4; ++m) _Pragma("unroll") for (int k = 0; k < 2; ++k) dst[m][k] = *(const LAS bf16x8*)(lds + PG8_SA(b, h) + aoff + m * 2048 + k * 1024); } while (0)
; #define PG8_MMA(ai, bj, At, Bt) do { __builtin_amdgcn_s_setprio(1); _Pragma("unroll") for (int m = 0; m < 4; ++m) _Pragma("unroll") for (int n = 0; n < 2; ++n) _Pragma("unroll") for (int k = 0; k < 2; ++k) \
;         acc[ai][bj][m][n] = __builtin_amdgcn_mfma_f32_16x16x32_bf16(Bt[n][k], At[m][k], acc[ai][bj][m][n], 0, 0, 0); __builtin_amdgcn_s_setprio(0); } while (0)
; #define PG8_WAIT_V(n) asm volatile("s_waitcnt vmcnt(" #n ")" ::: "memory")
; #define PG8_WAIT_L(n) asm volatile("s_waitcnt lgkmcnt(" #n ")" ::: "memory")
; #define PG8_BAR __builtin_amdgcn_s_barrier()
; #define PG8_SCHED __builtin_amdgcn_sched_barrier(0)
; template <class Epi, class Sched>
; __device__ __forceinline__ void gemm_phase(LAS unsigned char* lds, const Sched& S, const Epi& E) {
;     ...
;             PG8_WAIT_V(8); PG8_WAIT_L(0); PG8_BAR; PG8_MMA(0, 0, At, B0); PG8_MMA(0, 1, At, B1); PG8_BAR; PG8_SCHED;
;             PG8_LDA(At, 0, 1); PG8_STAGE(PG8_SB(0, 0), b2, vB2, hB2 / 2); PG8_STAGE(PG8_SB(0, 1), b2 + hB2, vB2, hB2 / 2); PG8_STAGE(PG8_SA(0, 0), a2, vA2, hA2 / 2);
.Lpeel_join_30522_1:
	s_barrier
	v_mfma_f32_16x16x32_bf16 v[120:123], v[144:147], v[178:181], 0
	v_mfma_f32_16x16x32_bf16 v[116:119], v[152:155], v[178:181], 0
	v_mfma_f32_16x16x32_bf16 v[104:107], v[144:147], v[186:189], 0
	v_mfma_f32_16x16x32_bf16 v[100:103], v[152:155], v[186:189], 0
	v_mfma_f32_16x16x32_bf16 v[88:91], v[144:147], v[194:197], 0
	v_mfma_f32_16x16x32_bf16 v[84:87], v[152:155], v[194:197], 0
	v_mfma_f32_16x16x32_bf16 v[72:75], v[144:147], v[202:205], 0
	v_mfma_f32_16x16x32_bf16 v[68:71], v[152:155], v[202:205], 0
	v_mfma_f32_16x16x32_bf16 v[120:123], v[148:151], v[182:185], v[120:123]
	v_mfma_f32_16x16x32_bf16 v[116:119], v[156:159], v[182:185], v[116:119]
	v_mfma_f32_16x16x32_bf16 v[104:107], v[148:151], v[190:193], v[104:107]
	v_mfma_f32_16x16x32_bf16 v[100:103], v[156:159], v[190:193], v[100:103]
	v_mfma_f32_16x16x32_bf16 v[88:91], v[148:151], v[198:201], v[88:91]
	v_mfma_f32_16x16x32_bf16 v[84:87], v[156:159], v[198:201], v[84:87]
	v_mfma_f32_16x16x32_bf16 v[72:75], v[148:151], v[206:209], v[72:75]
	v_mfma_f32_16x16x32_bf16 v[68:71], v[156:159], v[206:209], v[68:71]
	v_mfma_f32_16x16x32_bf16 v[124:127], v[160:163], v[178:181], 0
	v_mfma_f32_16x16x32_bf16 v[112:115], v[168:171], v[178:181], 0
	v_mfma_f32_16x16x32_bf16 v[108:111], v[160:163], v[186:189], 0
	v_mfma_f32_16x16x32_bf16 v[96:99], v[168:171], v[186:189], 0
	v_mfma_f32_16x16x32_bf16 v[92:95], v[160:163], v[194:197], 0
	v_mfma_f32_16x16x32_bf16 v[80:83], v[168:171], v[194:197], 0
	v_mfma_f32_16x16x32_bf16 v[76:79], v[160:163], v[202:205], 0
	v_mfma_f32_16x16x32_bf16 v[64:67], v[168:171], v[202:205], 0
	v_mfma_f32_16x16x32_bf16 v[124:127], v[164:167], v[182:185], v[124:127]
	v_mfma_f32_16x16x32_bf16 v[112:115], v[172:175], v[182:185], v[112:115]
	v_mfma_f32_16x16x32_bf16 v[108:111], v[164:167], v[190:193], v[108:111]
	v_mfma_f32_16x16x32_bf16 v[96:99], v[172:175], v[190:193], v[96:99]
	v_mfma_f32_16x16x32_bf16 v[92:95], v[164:167], v[198:201], v[92:95]
	v_mfma_f32_16x16x32_bf16 v[80:83], v[172:175], v[198:201], v[80:83]
	v_mfma_f32_16x16x32_bf16 v[76:79], v[164:167], v[206:209], v[76:79]
	v_mfma_f32_16x16x32_bf16 v[64:67], v[172:175], v[206:209], v[64:67]
	s_add_i32 s63, s63, 2
	s_add_u32 s26, s26, 0x100
	s_addc_u32 s27, s27, 0
	s_add_u32 s61, s61, 0x100
	s_addc_u32 s62, s62, 0
	s_barrier
	s_add_u32 s66, s42, 0x20000
	ds_read_b128 v[178:181], v140 offset:16384
	ds_read_b128 v[182:185], v140 offset:17408
	ds_read_b128 v[186:189], v140 offset:18432
	ds_read_b128 v[190:193], v140 offset:19456
	ds_read_b128 v[194:197], v140 offset:20480
	ds_read_b128 v[198:201], v140 offset:21504
	ds_read_b128 v[202:205], v140 offset:22528
	ds_read_b128 v[206:209], v140 offset:23552
	s_mov_b32 m0, s35
	s_nop 0
	global_load_lds_dwordx4 v135, s[42:43]
	s_mov_b32 m0, s36
	s_addc_u32 s67, s43, 0
	global_load_lds_dwordx4 v135, s[66:67]
	s_add_u32 s66, s42, 0x40000
	s_mov_b32 m0, s37
	s_addc_u32 s67, s43, 0
	global_load_lds_dwordx4 v135, s[66:67]
	s_add_u32 s66, s42, 0x60000
	s_mov_b32 m0, s44
	s_addc_u32 s67, s43, 0
	global_load_lds_dwordx4 v135, s[66:67]
	s_mov_b32 m0, s34
	s_nop 0
	global_load_lds_dwordx4 v134, s[38:39]
	s_add_u32 s66, s38, 0x20000
	s_mov_b32 m0, s45
	s_addc_u32 s67, s39, 0
	global_load_lds_dwordx4 v134, s[66:67]
	s_cmp_eq_u32 s21, 0
	s_cbranch_scc1 .Lpeel_strict_30522_0
	s_waitcnt vmcnt(16) lgkmcnt(0)
	s_branch .Lpeel_join_30522_0

; #define PG8_MMA(ai, bj, At, Bt) do { __builtin_amdgcn_s_setprio(1); _Pragma("unroll") for (int m = 0; m < 4; ++m) _Pragma("unroll") for (int n = 0; n < 2; ++n) _Pragma("unroll") for (int k = 0; k < 2; ++k) \
;         acc[ai][bj][m][n] = __builtin_amdgcn_mfma_f32_16x16x32_bf16(Bt[n][k], At[m][k], acc[ai][bj][m][n], 0, 0, 0); __builtin_amdgcn_s_setprio(0); } while (0)
; #define PG8_WAIT_V(n) asm volatile("s_waitcnt vmcnt(" #n ")" ::: "memory")
; #define PG8_WAIT_L(n) asm volatile("s_waitcnt lgkmcnt(" #n ")" ::: "memory")
; #define PG8_BAR __builtin_amdgcn_s_barrier()
; #define PG8_SCHED __builtin_amdgcn_sched_barrier(0)
; template <class Epi, class Sched>
; __device__ __forceinline__ void gemm_phase(LAS unsigned char* lds, const Sched& S, const Epi& E) {
;     ...
;             PG8_WAIT_V(8); PG8_WAIT_L(0); PG8_BAR; PG8_MMA(1, 0, At, B0); PG8_MMA(1, 1, At, B1); PG8_BAR; PG8_SCHED;
.Lpeel_join_30522_0:
	s_barrier
	v_mfma_f32_16x16x32_bf16 v[56:59], v[144:147], v[178:181], 0
	v_mfma_f32_16x16x32_bf16 v[52:55], v[152:155], v[178:181], 0
	v_mfma_f32_16x16x32_bf16 v[40:43], v[144:147], v[186:189], 0
	v_mfma_f32_16x16x32_bf16 v[36:39], v[152:155], v[186:189], 0
	v_mfma_f32_16x16x32_bf16 v[24:27], v[144:147], v[194:197], 0
	v_mfma_f32_16x16x32_bf16 v[20:23], v[152:155], v[194:197], 0
	v_mfma_f32_16x16x32_bf16 v[8:11], v[144:147], v[202:205], 0
	v_mfma_f32_16x16x32_bf16 v[4:7], v[152:155], v[202:205], 0
	v_mfma_f32_16x16x32_bf16 v[56:59], v[148:151], v[182:185], v[56:59]
	v_mfma_f32_16x16x32_bf16 v[52:55], v[156:159], v[182:185], v[52:55]
	v_mfma_f32_16x16x32_bf16 v[40:43], v[148:151], v[190:193], v[40:43]
	v_mfma_f32_16x16x32_bf16 v[36:39], v[156:159], v[190:193], v[36:39]
	v_mfma_f32_16x16x32_bf16 v[24:27], v[148:151], v[198:201], v[24:27]
	v_mfma_f32_16x16x32_bf16 v[20:23], v[156:159], v[198:201], v[20:23]
	v_mfma_f32_16x16x32_bf16 v[8:11], v[148:151], v[206:209], v[8:11]
	v_mfma_f32_16x16x32_bf16 v[4:7], v[156:159], v[206:209], v[4:7]
	v_mfma_f32_16x16x32_bf16 v[60:63], v[160:163], v[178:181], 0
	v_mfma_f32_16x16x32_bf16 v[48:51], v[168:171], v[178:181], 0
	v_mfma_f32_16x16x32_bf16 v[44:47], v[160:163], v[186:189], 0
	v_mfma_f32_16x16x32_bf16 v[32:35], v[168:171], v[186:189], 0
	v_mfma_f32_16x16x32_bf16 v[28:31], v[160:163], v[194:197], 0
	v_mfma_f32_16x16x32_bf16 v[16:19], v[168:171], v[194:197], 0
	v_mfma_f32_16x16x32_bf16 v[12:15], v[160:163], v[202:205], 0
	v_mfma_f32_16x16x32_bf16 v[0:3], v[168:171], v[202:205], 0
	v_mfma_f32_16x16x32_bf16 v[60:63], v[164:167], v[182:185], v[60:63]
	v_mfma_f32_16x16x32_bf16 v[48:51], v[172:175], v[182:185], v[48:51]
	v_mfma_f32_16x16x32_bf16 v[44:47], v[164:167], v[190:193], v[44:47]
	v_mfma_f32_16x16x32_bf16 v[32:35], v[172:175], v[190:193], v[32:35]
	v_mfma_f32_16x16x32_bf16 v[28:31], v[164:167], v[198:201], v[28:31]
	v_mfma_f32_16x16x32_bf16 v[16:19], v[172:175], v[198:201], v[16:19]
	v_mfma_f32_16x16x32_bf16 v[12:15], v[164:167], v[206:209], v[12:15]
	v_mfma_f32_16x16x32_bf16 v[0:3], v[172:175], v[206:209], v[0:3]
	s_barrier
	s_branch .Lpeel_mid_30522

; __device__ __forceinline__ u32x4 pack8(const f32x4 a, const f32x4 b) { u32x4 w; w.x = pk2(a[0], a[1]); w.y = pk2(a[2], a[3]); w.z = pk2(b[0], b[1]); w.w = pk2(b[2], b[3]); return w; }
; __device__ __forceinline__ f32x4 vsig(const f32x4 x) {
;     const f32x4 t = x * (-1.4426950409f); f32x4 d;
; #pragma unroll
;     for (int e = 0; e < 4; ++e) d[e] = __builtin_amdgcn_exp2f(t[e]);
;     d = d + 1.0f; f32x4 r;
; #pragma unroll
;     for (int e = 0; e < 4; ++e) r[e] = __builtin_amdgcn_rcpf(d[e]);
;     return r;
; }
;     __device__ __forceinline__ bool operator()(EPI_ARGS) const {
;             const int pt = u.pn;
; #pragma unroll
;             for (int ai = 0; ai < 2; ++ai)
; #pragma unroll
;                 for (int m = 0; m < 4; ++m) {
;                     const size_t row = (size_t)u.pm * 256 + ROWLOC(ai, m);
;                     const f32x4 o0 = acc[ai][0][m][0] * vsig(acc[ai][1][m][0]), o1 = acc[ai][0][m][1] * vsig(acc[ai][1][m][1]);
;                     *(u32x4*)(y + row * D + pt * 128 + 32 * wc + 8 * fq) = pack8(o0, o1);
;                 }
.LBB0_1020:
	s_lshl_b32 s26, s20, 19
	s_lshl_b32 s38, s60, 8
	s_add_i32 s26, s26, s38
	s_add_i32 s26, s26, s6
	v_add_u32_e32 v146, s50, v136
	v_lshlrev_b32_e32 v147, 4, v137
	v_lshl_add_u32 v146, v146, 11, v147
	v_mov_b32_e32 v144, 0xbfb8aa3b
	v_mov_b32_e32 v145, 0xbfb8aa3b
	v_add_u32_e32 v146, s26, v146
	v_pk_mul_f32 v[124:125], v[124:125], v[144:145]
	v_pk_mul_f32 v[126:127], v[126:127], v[144:145]
	v_pk_mul_f32 v[112:113], v[112:113], v[144:145]
	v_pk_mul_f32 v[114:115], v[114:115], v[144:145]
	v_exp_f32_e32 v124, v124
	v_exp_f32_e32 v125, v125
	v_exp_f32_e32 v126, v126
	v_exp_f32_e32 v127, v127
	v_exp_f32_e32 v112, v112
	v_exp_f32_e32 v113, v113
	v_exp_f32_e32 v114, v114
	v_exp_f32_e32 v115, v115
	v_pk_add_f32 v[124:125], v[124:125], 1.0 op_sel_hi:[1,0]
	v_pk_add_f32 v[126:127], v[126:127], 1.0 op_sel_hi:[1,0]
	v_pk_add_f32 v[112:113], v[112:113], 1.0 op_sel_hi:[1,0]
	v_pk_add_f32 v[114:115], v[114:115], 1.0 op_sel_hi:[1,0]
	v_rcp_f32_e32 v124, v124
	v_rcp_f32_e32 v125, v125
	v_rcp_f32_e32 v126, v126
	v_rcp_f32_e32 v127, v127
	v_rcp_f32_e32 v112, v112
	v_rcp_f32_e32 v113, v113
	v_rcp_f32_e32 v114, v114
	v_rcp_f32_e32 v115, v115
	v_pk_mul_f32 v[124:125], v[120:121], v[124:125]
	v_pk_mul_f32 v[126:127], v[122:123], v[126:127]
	v_pk_mul_f32 v[112:113], v[116:117], v[112:113]
	v_pk_mul_f32 v[114:115], v[118:119], v[114:115]
	v_cvt_pk_bf16_f32 v120, v124, v125
	v_cvt_pk_bf16_f32 v121, v126, v127
	v_cvt_pk_bf16_f32 v122, v112, v113
	v_cvt_pk_bf16_f32 v123, v114, v115
	global_store_dwordx4 v146, v[120:123], s[48:49]
	v_pk_mul_f32 v[108:109], v[108:109], v[144:145]
	v_pk_mul_f32 v[110:111], v[110:111], v[144:145]
	v_pk_mul_f32 v[96:97], v[96:97], v[144:145]
	v_pk_mul_f32 v[98:99], v[98:99], v[144:145]
	v_exp_f32_e32 v108, v108
	v_exp_f32_e32 v109, v109
	v_exp_f32_e32 v110, v110
	v_exp_f32_e32 v111, v111
	v_exp_f32_e32 v96, v96
	v_exp_f32_e32 v97, v97
	v_exp_f32_e32 v98, v98
	v_exp_f32_e32 v99, v99
	v_pk_add_f32 v[108:109], v[108:109], 1.0 op_sel_hi:[1,0]
	v_pk_add_f32 v[110:111], v[110:111], 1.0 op_sel_hi:[1,0]
	v_pk_add_f32 v[96:97], v[96:97], 1.0 op_sel_hi:[1,0]
	v_pk_add_f32 v[98:99], v[98:99], 1.0 op_sel_hi:[1,0]
	v_rcp_f32_e32 v108, v108
	v_rcp_f32_e32 v109, v109
	v_rcp_f32_e32 v110, v110
	v_rcp_f32_e32 v111, v111
	v_rcp_f32_e32 v96, v96
	v_rcp_f32_e32 v97, v97
	v_rcp_f32_e32 v98, v98
	v_rcp_f32_e32 v99, v99
	v_pk_mul_f32 v[108:109], v[104:105], v[108:109]
	v_pk_mul_f32 v[110:111], v[106:107], v[110:111]
	v_pk_mul_f32 v[96:97], v[100:101], v[96:97]
	v_pk_mul_f32 v[98:99], v[102:103], v[98:99]
	v_cvt_pk_bf16_f32 v104, v108, v109
	v_cvt_pk_bf16_f32 v105, v110, v111
	v_cvt_pk_bf16_f32 v106, v96, v97
	v_cvt_pk_bf16_f32 v107, v98, v99
	v_add_u32_e32 v147, 0x8000, v146
	global_store_dwordx4 v147, v[104:107], s[48:49]
	v_pk_mul_f32 v[92:93], v[92:93], v[144:145]
	v_pk_mul_f32 v[94:95], v[94:95], v[144:145]
	v_pk_mul_f32 v[80:81], v[80:81], v[144:145]
	v_pk_mul_f32 v[82:83], v[82:83], v[144:145]
	v_exp_f32_e32 v92, v92
	v_exp_f32_e32 v93, v93
	v_exp_f32_e32 v94, v94
	v_exp_f32_e32 v95, v95
	v_exp_f32_e32 v80, v80
	v_exp_f32_e32 v81, v81
	v_exp_f32_e32 v82, v82
	v_exp_f32_e32 v83, v83
	v_pk_add_f32 v[92:93], v[92:93], 1.0 op_sel_hi:[1,0]
	v_pk_add_f32 v[94:95], v[94:95], 1.0 op_sel_hi:[1,0]
	v_pk_add_f32 v[80:81], v[80:81], 1.0 op_sel_hi:[1,0]
	v_pk_add_f32 v[82:83], v[82:83], 1.0 op_sel_hi:[1,0]
	v_rcp_f32_e32 v92, v92
	v_rcp_f32_e32 v93, v93
	v_rcp_f32_e32 v94, v94
	v_rcp_f32_e32 v95, v95
	v_rcp_f32_e32 v80, v80
	v_rcp_f32_e32 v81, v81
	v_rcp_f32_e32 v82, v82
	v_rcp_f32_e32 v83, v83
	v_pk_mul_f32 v[92:93], v[88:89], v[92:93]
	v_pk_mul_f32 v[94:95], v[90:91], v[94:95]
	v_pk_mul_f32 v[80:81], v[84:85], v[80:81]
	v_pk_mul_f32 v[82:83], v[86:87], v[82:83]
	v_cvt_pk_bf16_f32 v88, v92, v93
	v_cvt_pk_bf16_f32 v89, v94, v95
	v_cvt_pk_bf16_f32 v90, v80, v81
	v_cvt_pk_bf16_f32 v91, v82, v83
	v_add_u32_e32 v147, 0x10000, v146
	global_store_dwordx4 v147, v[88:91], s[48:49]
	v_pk_mul_f32 v[76:77], v[76:77], v[144:145]
	v_pk_mul_f32 v[78:79], v[78:79], v[144:145]
	v_pk_mul_f32 v[64:65], v[64:65], v[144:145]
	v_pk_mul_f32 v[66:67], v[66:67], v[144:145]
	v_exp_f32_e32 v76, v76
	v_exp_f32_e32 v77, v77
	v_exp_f32_e32 v78, v78
	v_exp_f32_e32 v79, v79
	v_exp_f32_e32 v64, v64
	v_exp_f32_e32 v65, v65
	v_exp_f32_e32 v66, v66
	v_exp_f32_e32 v67, v67
	v_pk_add_f32 v[76:77], v[76:77], 1.0 op_sel_hi:[1,0]
	v_pk_add_f32 v[78:79], v[78:79], 1.0 op_sel_hi:[1,0]
	v_pk_add_f32 v[64:65], v[64:65], 1.0 op_sel_hi:[1,0]
	v_pk_add_f32 v[66:67], v[66:67], 1.0 op_sel_hi:[1,0]
	v_rcp_f32_e32 v76, v76
	v_rcp_f32_e32 v77, v77
	v_rcp_f32_e32 v78, v78
	v_rcp_f32_e32 v79, v79
	v_rcp_f32_e32 v64, v64
	v_rcp_f32_e32 v65, v65
	v_rcp_f32_e32 v66, v66
	v_rcp_f32_e32 v67, v67
	v_pk_mul_f32 v[76:77], v[72:73], v[76:77]
	v_pk_mul_f32 v[78:79], v[74:75], v[78:79]
	v_pk_mul_f32 v[64:65], v[68:69], v[64:65]
	v_pk_mul_f32 v[66:67], v[70:71], v[66:67]
	v_cvt_pk_bf16_f32 v72, v76, v77
	v_cvt_pk_bf16_f32 v73, v78, v79
; __device__ __forceinline__ u32x4 pack8(const f32x4 a, const f32x4 b) { u32x4 w; w.x = pk2(a[0], a[1]); w.y = pk2(a[2], a[3]); w.z = pk2(b[0], b[1]); w.w = pk2(b[2], b[3]); return w; }
; __device__ __forceinline__ f32x4 vsig(const f32x4 x) {
;     const f32x4 t = x * (-1.4426950409f); f32x4 d;
; #pragma unroll
;     for (int e = 0; e < 4; ++e) d[e] = __builtin_amdgcn_exp2f(t[e]);
;     d = d + 1.0f; f32x4 r;
; #pragma unroll
;     for (int e = 0; e < 4; ++e) r[e] = __builtin_amdgcn_rcpf(d[e]);
;     return r;
; }
;     __device__ __forceinline__ bool operator()(EPI_ARGS) const {
;             const int pt = u.pn;
; #pragma unroll
;             for (int ai = 0; ai < 2; ++ai)
; #pragma unroll
;                 for (int m = 0; m < 4; ++m) {
;                     const size_t row = (size_t)u.pm * 256 + ROWLOC(ai, m);
;                     const f32x4 o0 = acc[ai][0][m][0] * vsig(acc[ai][1][m][0]), o1 = acc[ai][0][m][1] * vsig(acc[ai][1][m][1]);
;                     *(u32x4*)(y + row * D + pt * 128 + 32 * wc + 8 * fq) = pack8(o0, o1);
;                 }
	v_cvt_pk_bf16_f32 v74, v64, v65
	v_cvt_pk_bf16_f32 v75, v66, v67
	v_add_u32_e32 v147, 0x18000, v146
	global_store_dwordx4 v147, v[72:75], s[48:49]
	v_pk_mul_f32 v[60:61], v[60:61], v[144:145]
	v_pk_mul_f32 v[62:63], v[62:63], v[144:145]
	v_pk_mul_f32 v[48:49], v[48:49], v[144:145]
	v_pk_mul_f32 v[50:51], v[50:51], v[144:145]
	v_exp_f32_e32 v60, v60
	v_exp_f32_e32 v61, v61
	v_exp_f32_e32 v62, v62
	v_exp_f32_e32 v63, v63
	v_exp_f32_e32 v48, v48
	v_exp_f32_e32 v49, v49
	v_exp_f32_e32 v50, v50
	v_exp_f32_e32 v51, v51
	v_pk_add_f32 v[60:61], v[60:61], 1.0 op_sel_hi:[1,0]
	v_pk_add_f32 v[62:63], v[62:63], 1.0 op_sel_hi:[1,0]
	v_pk_add_f32 v[48:49], v[48:49], 1.0 op_sel_hi:[1,0]
	v_pk_add_f32 v[50:51], v[50:51], 1.0 op_sel_hi:[1,0]
	v_rcp_f32_e32 v60, v60
	v_rcp_f32_e32 v61, v61
	v_rcp_f32_e32 v62, v62
	v_rcp_f32_e32 v63, v63
	v_rcp_f32_e32 v48, v48
	v_rcp_f32_e32 v49, v49
	v_rcp_f32_e32 v50, v50
	v_rcp_f32_e32 v51, v51
	v_pk_mul_f32 v[60:61], v[56:57], v[60:61]
	v_pk_mul_f32 v[62:63], v[58:59], v[62:63]
	v_pk_mul_f32 v[48:49], v[52:53], v[48:49]
	v_pk_mul_f32 v[50:51], v[54:55], v[50:51]
	v_cvt_pk_bf16_f32 v56, v60, v61
	v_cvt_pk_bf16_f32 v57, v62, v63
	v_cvt_pk_bf16_f32 v58, v48, v49
	v_cvt_pk_bf16_f32 v59, v50, v51
	v_add_u32_e32 v147, 0x40000, v146
	global_store_dwordx4 v147, v[56:59], s[48:49]
	v_pk_mul_f32 v[44:45], v[44:45], v[144:145]
	v_pk_mul_f32 v[46:47], v[46:47], v[144:145]
	v_pk_mul_f32 v[32:33], v[32:33], v[144:145]
	v_pk_mul_f32 v[34:35], v[34:35], v[144:145]
	v_exp_f32_e32 v44, v44
	v_exp_f32_e32 v45, v45
	v_exp_f32_e32 v46, v46
	v_exp_f32_e32 v47, v47
	v_exp_f32_e32 v32, v32
	v_exp_f32_e32 v33, v33
	v_exp_f32_e32 v34, v34
	v_exp_f32_e32 v35, v35
	v_pk_add_f32 v[44:45], v[44:45], 1.0 op_sel_hi:[1,0]
	v_pk_add_f32 v[46:47], v[46:47], 1.0 op_sel_hi:[1,0]
	v_pk_add_f32 v[32:33], v[32:33], 1.0 op_sel_hi:[1,0]
	v_pk_add_f32 v[34:35], v[34:35], 1.0 op_sel_hi:[1,0]
	v_rcp_f32_e32 v44, v44
	v_rcp_f32_e32 v45, v45
	v_rcp_f32_e32 v46, v46
	v_rcp_f32_e32 v47, v47
	v_rcp_f32_e32 v32, v32
	v_rcp_f32_e32 v33, v33
	v_rcp_f32_e32 v34, v34
	v_rcp_f32_e32 v35, v35
	v_pk_mul_f32 v[44:45], v[40:41], v[44:45]
	v_pk_mul_f32 v[46:47], v[42:43], v[46:47]
	v_pk_mul_f32 v[32:33], v[36:37], v[32:33]
	v_pk_mul_f32 v[34:35], v[38:39], v[34:35]
	v_cvt_pk_bf16_f32 v40, v44, v45
	v_cvt_pk_bf16_f32 v41, v46, v47
	v_cvt_pk_bf16_f32 v42, v32, v33
	v_cvt_pk_bf16_f32 v43, v34, v35
	v_add_u32_e32 v147, 0x48000, v146
	global_store_dwordx4 v147, v[40:43], s[48:49]
	v_pk_mul_f32 v[28:29], v[28:29], v[144:145]
	v_pk_mul_f32 v[30:31], v[30:31], v[144:145]
	v_pk_mul_f32 v[16:17], v[16:17], v[144:145]
	v_pk_mul_f32 v[18:19], v[18:19], v[144:145]
	v_exp_f32_e32 v28, v28
	v_exp_f32_e32 v29, v29
	v_exp_f32_e32 v30, v30
	v_exp_f32_e32 v31, v31
	v_exp_f32_e32 v16, v16
	v_exp_f32_e32 v17, v17
	v_exp_f32_e32 v18, v18
	v_exp_f32_e32 v19, v19
	v_pk_add_f32 v[28:29], v[28:29], 1.0 op_sel_hi:[1,0]
	v_pk_add_f32 v[30:31], v[30:31], 1.0 op_sel_hi:[1,0]
	v_pk_add_f32 v[16:17], v[16:17], 1.0 op_sel_hi:[1,0]
	v_pk_add_f32 v[18:19], v[18:19], 1.0 op_sel_hi:[1,0]
	v_rcp_f32_e32 v28, v28
	v_rcp_f32_e32 v29, v29
	v_rcp_f32_e32 v30, v30
	v_rcp_f32_e32 v31, v31
	v_rcp_f32_e32 v16, v16
	v_rcp_f32_e32 v17, v17
	v_rcp_f32_e32 v18, v18
	v_rcp_f32_e32 v19, v19
	v_pk_mul_f32 v[28:29], v[24:25], v[28:29]
	v_pk_mul_f32 v[30:31], v[26:27], v[30:31]
	v_pk_mul_f32 v[16:17], v[20:21], v[16:17]
	v_pk_mul_f32 v[18:19], v[22:23], v[18:19]
	v_cvt_pk_bf16_f32 v24, v28, v29
	v_cvt_pk_bf16_f32 v25, v30, v31
	v_cvt_pk_bf16_f32 v26, v16, v17
	v_cvt_pk_bf16_f32 v27, v18, v19
	v_add_u32_e32 v147, 0x50000, v146
	global_store_dwordx4 v147, v[24:27], s[48:49]
	v_pk_mul_f32 v[12:13], v[12:13], v[144:145]
	v_pk_mul_f32 v[14:15], v[14:15], v[144:145]
	v_pk_mul_f32 v[0:1], v[0:1], v[144:145]
	v_pk_mul_f32 v[2:3], v[2:3], v[144:145]
	v_exp_f32_e32 v12, v12
	v_exp_f32_e32 v13, v13
	v_exp_f32_e32 v14, v14
	v_exp_f32_e32 v15, v15
	v_exp_f32_e32 v0, v0
	v_exp_f32_e32 v1, v1
	v_exp_f32_e32 v2, v2
	v_exp_f32_e32 v3, v3
	v_pk_add_f32 v[12:13], v[12:13], 1.0 op_sel_hi:[1,0]
	v_pk_add_f32 v[14:15], v[14:15], 1.0 op_sel_hi:[1,0]
	v_pk_add_f32 v[0:1], v[0:1], 1.0 op_sel_hi:[1,0]
	v_pk_add_f32 v[2:3], v[2:3], 1.0 op_sel_hi:[1,0]
	v_rcp_f32_e32 v12, v12
	v_rcp_f32_e32 v13, v13
	v_rcp_f32_e32 v14, v14
	v_rcp_f32_e32 v15, v15
	v_rcp_f32_e32 v0, v0
	v_rcp_f32_e32 v1, v1
	v_rcp_f32_e32 v2, v2
	v_rcp_f32_e32 v3, v3
	v_pk_mul_f32 v[12:13], v[8:9], v[12:13]
	v_pk_mul_f32 v[14:15], v[10:11], v[14:15]
	v_pk_mul_f32 v[0:1], v[4:5], v[0:1]
	v_pk_mul_f32 v[2:3], v[6:7], v[2:3]
	v_cvt_pk_bf16_f32 v8, v12, v13
	v_cvt_pk_bf16_f32 v9, v14, v15
	v_cvt_pk_bf16_f32 v10, v0, v1
	v_cvt_pk_bf16_f32 v11, v2, v3
	v_add_u32_e32 v147, 0x58000, v146
	global_store_dwordx4 v147, v[8:11], s[48:49]
	s_andn2_b64 vcc, exec, s[10:11]
	s_mov_b64 s[10:11], -1
	s_cbranch_vccnz .LBB0_1003
	s_andn2_b64 vcc, exec, s[12:13]
	s_cbranch_vccnz .LBB0_1002
	s_barrier
	s_branch .LBB0_1002

; #define PG8_STAGE(bufoff, gbase, voff, p64) do { _Pragma("unroll") for (int _i = 0; _i < 2; ++_i) { \
;         const char* _gb = (const char*)(gbase) + (size_t)_i * (p64); const unsigned _la = ldsbase + (unsigned)(bufoff) + (unsigned)_i * 8192u; \
;         asm volatile("s_mov_b32 m0, %0\n\ts_nop 0\n\tglobal_load_lds_dwordx4 %1, %2" :: "s"(_la), "v"(voff), "s"(_gb) : "memory"); } } while (0)
; #define PG8_LDA(dst, b, h) do { _Pragma("unroll") for (int m = 0; m < 4; ++m) _Pragma("unroll") for (int k = 0; k < 2; ++k) dst[m][k] = *(const LAS bf16x8*)(lds + PG8_SA(b, h) + aoff + m * 2048 + k * 1024); } while (0)
; #define PG8_LDB(dst, b, h) do { _Pragma("unroll") for (int n = 0; n < 2; ++n) _Pragma("unroll") for (int k = 0; k < 2; ++k) dst[n][k] = *(const LAS bf16x8*)(lds + PG8_SB(b, h) + boff + n * 2048 + k * 1024); } while (0)
; #define PG8_MMA(ai, bj, At, Bt) do { __builtin_amdgcn_s_setprio(1); _Pragma("unroll") for (int m = 0; m < 4; ++m) _Pragma("unroll") for (int n = 0; n < 2; ++n) _Pragma("unroll") for (int k = 0; k < 2; ++k) \
;         acc[ai][bj][m][n] = __builtin_amdgcn_mfma_f32_16x16x32_bf16(Bt[n][k], At[m][k], acc[ai][bj][m][n], 0, 0, 0); __builtin_amdgcn_s_setprio(0); } while (0)
; #define PG8_WAIT_V(n) asm volatile("s_waitcnt vmcnt(" #n ")" ::: "memory")
; #define PG8_WAIT_L(n) asm volatile("s_waitcnt lgkmcnt(" #n ")" ::: "memory")
; #define PG8_BAR __builtin_amdgcn_s_barrier()
; #define PG8_SCHED __builtin_amdgcn_sched_barrier(0)
; template <class Epi, class Sched>
; __device__ __forceinline__ void gemm_phase(LAS unsigned char* lds, const Sched& S, const Epi& E) {
;     ...
;             PG8_LDB(B0, 0, 0); PG8_LDB(B1, 0, 1); PG8_SCHED; PG8_LDA(At, 0, 0); PG8_STAGE(PG8_SA(1, 1), a1 + hA, voffA, hA / 2);
;             PG8_WAIT_V(8); PG8_WAIT_L(0); PG8_BAR; PG8_MMA(0, 0, At, B0); PG8_MMA(0, 1, At, B1); PG8_BAR; PG8_SCHED;
.LBB0_1088:
	s_add_u32 s38, s38, 0x80080
	s_addc_u32 s39, s39, 0
	s_add_u32 s60, s40, 0x100
	s_addc_u32 s61, s41, 0
	s_mov_b32 s62, -2
	ds_read_b128 v[144:147], v138
	ds_read_b128 v[148:151], v138 offset:1024
	ds_read_b128 v[152:155], v138 offset:2048
	ds_read_b128 v[156:159], v138 offset:3072
	ds_read_b128 v[160:163], v139
	ds_read_b128 v[164:167], v139 offset:1024
	ds_read_b128 v[168:171], v139 offset:2048
	ds_read_b128 v[172:175], v139 offset:3072
	s_add_u32 s30, s38, 0xfff80080
	s_addc_u32 s40, s39, -1
	s_cmp_eq_u32 s62, 28
	s_cselect_b32 s41, s25, s40
	s_cselect_b32 s40, s24, s30
	s_cselect_b32 s44, s26, s60
	s_cselect_b32 s45, s27, s61
	s_add_u32 s42, s40, 0x80
	s_addc_u32 s43, s41, 0
	ds_read_b128 v[178:181], v140
	ds_read_b128 v[182:185], v140 offset:1024
	ds_read_b128 v[186:189], v140 offset:2048
	ds_read_b128 v[190:193], v140 offset:3072
	ds_read_b128 v[194:197], v140 offset:4096
	ds_read_b128 v[198:201], v140 offset:5120
	ds_read_b128 v[202:205], v140 offset:6144
	ds_read_b128 v[206:209], v140 offset:7168
	s_mov_b32 m0, s56
	s_nop 0
	global_load_lds_dwordx4 v134, s[38:39]
	s_add_u32 s66, s38, 0x40000
	s_mov_b32 m0, s57
	s_addc_u32 s67, s39, 0
	global_load_lds_dwordx4 v134, s[66:67]
	s_cmp_eq_u32 s23, 0
	s_cbranch_scc1 .Lpeel_strict_32192_1
	s_waitcnt vmcnt(24) lgkmcnt(0)
	s_branch .Lpeel_join_32192_1

; #define PG8_STAGE(bufoff, gbase, voff, p64) do { _Pragma("unroll") for (int _i = 0; _i < 2; ++_i) { \
;         const char* _gb = (const char*)(gbase) + (size_t)_i * (p64); const unsigned _la = ldsbase + (unsigned)(bufoff) + (unsigned)_i * 8192u; \
;         asm volatile("s_mov_b32 m0, %0\n\ts_nop 0\n\tglobal_load_lds_dwordx4 %1, %2" :: "s"(_la), "v"(voff), "s"(_gb) : "memory"); } } while (0)
; #define PG8_LDA(dst, b, h) do { _Pragma("unroll") for (int m = 0; m < 4; ++m) _Pragma("unroll") for (int k = 0; k < 2; ++k) dst[m][k] = *(const LAS bf16x8*)(lds + PG8_SA(b, h) + aoff + m * 2048 + k * 1024); } while (0)
; #define PG8_MMA(ai, bj, At, Bt) do { __builtin_amdgcn_s_setprio(1); _Pragma("unroll") for (int m = 0; m < 4; ++m) _Pragma("unroll") for (int n = 0; n < 2; ++n) _Pragma("unroll") for (int k = 0; k < 2; ++k) \
;         acc[ai][bj][m][n] = __builtin_amdgcn_mfma_f32_16x16x32_bf16(Bt[n][k], At[m][k], acc[ai][bj][m][n], 0, 0, 0); __builtin_amdgcn_s_setprio(0); } while (0)
; #define PG8_WAIT_V(n) asm volatile("s_waitcnt vmcnt(" #n ")" ::: "memory")
; #define PG8_WAIT_L(n) asm volatile("s_waitcnt lgkmcnt(" #n ")" ::: "memory")
; #define PG8_BAR __builtin_amdgcn_s_barrier()
; #define PG8_SCHED __builtin_amdgcn_sched_barrier(0)
; template <class Epi, class Sched>
; __device__ __forceinline__ void gemm_phase(LAS unsigned char* lds, const Sched& S, const Epi& E) {
;     ...
;             PG8_WAIT_V(8); PG8_WAIT_L(0); PG8_BAR; PG8_MMA(0, 0, At, B0); PG8_MMA(0, 1, At, B1); PG8_BAR; PG8_SCHED;
;             PG8_LDA(At, 0, 1); PG8_STAGE(PG8_SB(0, 0), b2, vB2, hB2 / 2); PG8_STAGE(PG8_SB(0, 1), b2 + hB2, vB2, hB2 / 2); PG8_STAGE(PG8_SA(0, 0), a2, vA2, hA2 / 2);
.Lpeel_join_32192_1:
	s_barrier
	v_mfma_f32_16x16x32_bf16 v[124:127], v[144:147], v[178:181], 0
	v_mfma_f32_16x16x32_bf16 v[120:123], v[152:155], v[178:181], 0
	v_mfma_f32_16x16x32_bf16 v[116:119], v[144:147], v[186:189], 0
	v_mfma_f32_16x16x32_bf16 v[108:111], v[152:155], v[186:189], 0
	v_mfma_f32_16x16x32_bf16 v[100:103], v[144:147], v[194:197], 0
	v_mfma_f32_16x16x32_bf16 v[92:95], v[152:155], v[194:197], 0
	v_mfma_f32_16x16x32_bf16 v[84:87], v[144:147], v[202:205], 0
	v_mfma_f32_16x16x32_bf16 v[76:79], v[152:155], v[202:205], 0
	v_mfma_f32_16x16x32_bf16 v[124:127], v[148:151], v[182:185], v[124:127]
	v_mfma_f32_16x16x32_bf16 v[120:123], v[156:159], v[182:185], v[120:123]
	v_mfma_f32_16x16x32_bf16 v[116:119], v[148:151], v[190:193], v[116:119]
	v_mfma_f32_16x16x32_bf16 v[108:111], v[156:159], v[190:193], v[108:111]
	v_mfma_f32_16x16x32_bf16 v[100:103], v[148:151], v[198:201], v[100:103]
	v_mfma_f32_16x16x32_bf16 v[92:95], v[156:159], v[198:201], v[92:95]
	v_mfma_f32_16x16x32_bf16 v[84:87], v[148:151], v[206:209], v[84:87]
	v_mfma_f32_16x16x32_bf16 v[76:79], v[156:159], v[206:209], v[76:79]
	v_mfma_f32_16x16x32_bf16 v[112:115], v[160:163], v[178:181], 0
	v_mfma_f32_16x16x32_bf16 v[104:107], v[168:171], v[178:181], 0
	v_mfma_f32_16x16x32_bf16 v[96:99], v[160:163], v[186:189], 0
	v_mfma_f32_16x16x32_bf16 v[88:91], v[168:171], v[186:189], 0
	v_mfma_f32_16x16x32_bf16 v[80:83], v[160:163], v[194:197], 0
	v_mfma_f32_16x16x32_bf16 v[72:75], v[168:171], v[194:197], 0
	v_mfma_f32_16x16x32_bf16 v[68:71], v[160:163], v[202:205], 0
	v_mfma_f32_16x16x32_bf16 v[64:67], v[168:171], v[202:205], 0
	v_mfma_f32_16x16x32_bf16 v[112:115], v[164:167], v[182:185], v[112:115]
	v_mfma_f32_16x16x32_bf16 v[104:107], v[172:175], v[182:185], v[104:107]
	v_mfma_f32_16x16x32_bf16 v[96:99], v[164:167], v[190:193], v[96:99]
	v_mfma_f32_16x16x32_bf16 v[88:91], v[172:175], v[190:193], v[88:91]
	v_mfma_f32_16x16x32_bf16 v[80:83], v[164:167], v[198:201], v[80:83]
	v_mfma_f32_16x16x32_bf16 v[72:75], v[172:175], v[198:201], v[72:75]
	v_mfma_f32_16x16x32_bf16 v[68:71], v[164:167], v[206:209], v[68:71]
	v_mfma_f32_16x16x32_bf16 v[64:67], v[172:175], v[206:209], v[64:67]
	s_add_i32 s62, s62, 2
	s_add_u32 s38, s38, 0x100
	s_addc_u32 s39, s39, 0
	s_add_u32 s60, s60, 0x100
	s_addc_u32 s61, s61, 0
	s_barrier
	s_add_u32 s66, s44, 0x40000
	ds_read_b128 v[178:181], v140 offset:16384
	ds_read_b128 v[182:185], v140 offset:17408
	ds_read_b128 v[186:189], v140 offset:18432
	ds_read_b128 v[190:193], v140 offset:19456
	ds_read_b128 v[194:197], v140 offset:20480
	ds_read_b128 v[198:201], v140 offset:21504
	ds_read_b128 v[202:205], v140 offset:22528
	ds_read_b128 v[206:209], v140 offset:23552
	s_mov_b32 m0, s33
	s_nop 0
	global_load_lds_dwordx4 v135, s[44:45]
	s_mov_b32 m0, s34
	s_addc_u32 s67, s45, 0
	global_load_lds_dwordx4 v135, s[66:67]
	s_add_u32 s66, s44, 0x80000
	s_mov_b32 m0, s35
	s_addc_u32 s67, s45, 0
	global_load_lds_dwordx4 v135, s[66:67]
	s_add_u32 s66, s44, 0xc0000
	s_mov_b32 m0, s36
	s_addc_u32 s67, s45, 0
	global_load_lds_dwordx4 v135, s[66:67]
	s_mov_b32 m0, s31
	s_nop 0
	global_load_lds_dwordx4 v134, s[40:41]
	s_add_u32 s66, s40, 0x40000
	s_mov_b32 m0, s37
	s_addc_u32 s67, s41, 0
	global_load_lds_dwordx4 v134, s[66:67]
	s_cmp_eq_u32 s23, 0
	s_cbranch_scc1 .Lpeel_strict_32192_0
	s_waitcnt vmcnt(24) lgkmcnt(0)
	s_branch .Lpeel_join_32192_0

; #define PG8_MMA(ai, bj, At, Bt) do { __builtin_amdgcn_s_setprio(1); _Pragma("unroll") for (int m = 0; m < 4; ++m) _Pragma("unroll") for (int n = 0; n < 2; ++n) _Pragma("unroll") for (int k = 0; k < 2; ++k) \
;         acc[ai][bj][m][n] = __builtin_amdgcn_mfma_f32_16x16x32_bf16(Bt[n][k], At[m][k], acc[ai][bj][m][n], 0, 0, 0); __builtin_amdgcn_s_setprio(0); } while (0)
; #define PG8_WAIT_V(n) asm volatile("s_waitcnt vmcnt(" #n ")" ::: "memory")
; #define PG8_WAIT_L(n) asm volatile("s_waitcnt lgkmcnt(" #n ")" ::: "memory")
; #define PG8_BAR __builtin_amdgcn_s_barrier()
; #define PG8_SCHED __builtin_amdgcn_sched_barrier(0)
; template <class Epi, class Sched>
; __device__ __forceinline__ void gemm_phase(LAS unsigned char* lds, const Sched& S, const Epi& E) {
;     ...
;             PG8_WAIT_V(8); PG8_WAIT_L(0); PG8_BAR; PG8_MMA(1, 0, At, B0); PG8_MMA(1, 1, At, B1); PG8_BAR; PG8_SCHED;
.Lpeel_join_32192_0:
	s_barrier
	v_mfma_f32_16x16x32_bf16 v[60:63], v[144:147], v[178:181], 0
	v_mfma_f32_16x16x32_bf16 v[56:59], v[152:155], v[178:181], 0
	v_mfma_f32_16x16x32_bf16 v[52:55], v[144:147], v[186:189], 0
	v_mfma_f32_16x16x32_bf16 v[44:47], v[152:155], v[186:189], 0
	v_mfma_f32_16x16x32_bf16 v[36:39], v[144:147], v[194:197], 0
	v_mfma_f32_16x16x32_bf16 v[28:31], v[152:155], v[194:197], 0
	v_mfma_f32_16x16x32_bf16 v[20:23], v[144:147], v[202:205], 0
	v_mfma_f32_16x16x32_bf16 v[12:15], v[152:155], v[202:205], 0
	v_mfma_f32_16x16x32_bf16 v[60:63], v[148:151], v[182:185], v[60:63]
	v_mfma_f32_16x16x32_bf16 v[56:59], v[156:159], v[182:185], v[56:59]
	v_mfma_f32_16x16x32_bf16 v[52:55], v[148:151], v[190:193], v[52:55]
	v_mfma_f32_16x16x32_bf16 v[44:47], v[156:159], v[190:193], v[44:47]
	v_mfma_f32_16x16x32_bf16 v[36:39], v[148:151], v[198:201], v[36:39]
	v_mfma_f32_16x16x32_bf16 v[28:31], v[156:159], v[198:201], v[28:31]
	v_mfma_f32_16x16x32_bf16 v[20:23], v[148:151], v[206:209], v[20:23]
	v_mfma_f32_16x16x32_bf16 v[12:15], v[156:159], v[206:209], v[12:15]
	v_mfma_f32_16x16x32_bf16 v[48:51], v[160:163], v[178:181], 0
	v_mfma_f32_16x16x32_bf16 v[40:43], v[168:171], v[178:181], 0
	v_mfma_f32_16x16x32_bf16 v[32:35], v[160:163], v[186:189], 0
	v_mfma_f32_16x16x32_bf16 v[24:27], v[168:171], v[186:189], 0
	v_mfma_f32_16x16x32_bf16 v[16:19], v[160:163], v[194:197], 0
	v_mfma_f32_16x16x32_bf16 v[8:11], v[168:171], v[194:197], 0
	v_mfma_f32_16x16x32_bf16 v[4:7], v[160:163], v[202:205], 0
	v_mfma_f32_16x16x32_bf16 v[0:3], v[168:171], v[202:205], 0
	v_mfma_f32_16x16x32_bf16 v[48:51], v[164:167], v[182:185], v[48:51]
	v_mfma_f32_16x16x32_bf16 v[40:43], v[172:175], v[182:185], v[40:43]
	v_mfma_f32_16x16x32_bf16 v[32:35], v[164:167], v[190:193], v[32:35]
	v_mfma_f32_16x16x32_bf16 v[24:27], v[172:175], v[190:193], v[24:27]
	v_mfma_f32_16x16x32_bf16 v[16:19], v[164:167], v[198:201], v[16:19]
	v_mfma_f32_16x16x32_bf16 v[8:11], v[172:175], v[198:201], v[8:11]
	v_mfma_f32_16x16x32_bf16 v[4:7], v[164:167], v[206:209], v[4:7]
	v_mfma_f32_16x16x32_bf16 v[0:3], v[172:175], v[206:209], v[0:3]
	s_barrier
	s_branch .Lpeel_mid_32192

; __device__ __forceinline__ u32x4 pack8(const f32x4 a, const f32x4 b) { u32x4 w; w.x = pk2(a[0], a[1]); w.y = pk2(a[2], a[3]); w.z = pk2(b[0], b[1]); w.w = pk2(b[2], b[3]); return w; }
;     __device__ __forceinline__ bool operator()(EPI_ARGS) const {
; #pragma unroll
;         for (int ai = 0; ai < 2; ++ai)
; #pragma unroll
;             for (int m = 0; m < 4; ++m) {
;                 const size_t row = (size_t)u.pm * 256 + ROWLOC(ai, m);
; #pragma unroll
;                 for (int bj = 0; bj < 2; ++bj) *(u32x4*)(dst + row * ld + u.pn * 256 + COLLOC(bj)) = pack8(acc[ai][bj][m][0], acc[ai][bj][m][1]);
;             }
.LBB0_1098:
	s_lshl_b32 s38, s22, 19
	s_lshl_b32 s40, s59, 9
	s_add_i32 s38, s38, s40
	s_lshl_b32 s40, s49, 1
	s_add_i32 s38, s38, s40
	v_add_u32_e32 v144, s48, v136
	v_lshlrev_b32_e32 v145, 4, v137
	v_lshl_add_u32 v144, v144, 11, v145
	v_add_u32_e32 v144, s38, v144
	v_cvt_pk_bf16_f32 v124, v124, v125
	v_cvt_pk_bf16_f32 v125, v126, v127
	v_cvt_pk_bf16_f32 v126, v120, v121
	v_cvt_pk_bf16_f32 v127, v122, v123
	global_store_dwordx4 v144, v[124:127], s[14:15]
	v_cvt_pk_bf16_f32 v112, v112, v113
	v_cvt_pk_bf16_f32 v113, v114, v115
	v_cvt_pk_bf16_f32 v114, v104, v105
	v_cvt_pk_bf16_f32 v115, v106, v107
	global_store_dwordx4 v144, v[112:115], s[14:15] offset:256
	v_add_u32_e32 v145, 0x8000, v144
	v_cvt_pk_bf16_f32 v116, v116, v117
	v_cvt_pk_bf16_f32 v117, v118, v119
	v_cvt_pk_bf16_f32 v118, v108, v109
	v_cvt_pk_bf16_f32 v119, v110, v111
	global_store_dwordx4 v145, v[116:119], s[14:15]
	v_cvt_pk_bf16_f32 v96, v96, v97
	v_cvt_pk_bf16_f32 v97, v98, v99
	v_cvt_pk_bf16_f32 v98, v88, v89
	v_cvt_pk_bf16_f32 v99, v90, v91
	global_store_dwordx4 v145, v[96:99], s[14:15] offset:256
	v_add_u32_e32 v145, 0x10000, v144
	v_cvt_pk_bf16_f32 v100, v100, v101
	v_cvt_pk_bf16_f32 v101, v102, v103
	v_cvt_pk_bf16_f32 v102, v92, v93
	v_cvt_pk_bf16_f32 v103, v94, v95
	global_store_dwordx4 v145, v[100:103], s[14:15]
	v_cvt_pk_bf16_f32 v80, v80, v81
	v_cvt_pk_bf16_f32 v81, v82, v83
	v_cvt_pk_bf16_f32 v82, v72, v73
	v_cvt_pk_bf16_f32 v83, v74, v75
	global_store_dwordx4 v145, v[80:83], s[14:15] offset:256
	v_add_u32_e32 v145, 0x18000, v144
	v_cvt_pk_bf16_f32 v84, v84, v85
	v_cvt_pk_bf16_f32 v85, v86, v87
	v_cvt_pk_bf16_f32 v86, v76, v77
	v_cvt_pk_bf16_f32 v87, v78, v79
	global_store_dwordx4 v145, v[84:87], s[14:15]
	v_cvt_pk_bf16_f32 v68, v68, v69
	v_cvt_pk_bf16_f32 v69, v70, v71
	v_cvt_pk_bf16_f32 v70, v64, v65
	v_cvt_pk_bf16_f32 v71, v66, v67
	global_store_dwordx4 v145, v[68:71], s[14:15] offset:256
	v_add_u32_e32 v145, 0x40000, v144
	v_cvt_pk_bf16_f32 v60, v60, v61
	v_cvt_pk_bf16_f32 v61, v62, v63
	v_cvt_pk_bf16_f32 v62, v56, v57
	v_cvt_pk_bf16_f32 v63, v58, v59
	global_store_dwordx4 v145, v[60:63], s[14:15]
	v_cvt_pk_bf16_f32 v48, v48, v49
	v_cvt_pk_bf16_f32 v49, v50, v51
	v_cvt_pk_bf16_f32 v50, v40, v41
	v_cvt_pk_bf16_f32 v51, v42, v43
	global_store_dwordx4 v145, v[48:51], s[14:15] offset:256
	v_add_u32_e32 v145, 0x48000, v144
	v_cvt_pk_bf16_f32 v52, v52, v53
	v_cvt_pk_bf16_f32 v53, v54, v55
	v_cvt_pk_bf16_f32 v54, v44, v45
	v_cvt_pk_bf16_f32 v55, v46, v47
	global_store_dwordx4 v145, v[52:55], s[14:15]
	v_cvt_pk_bf16_f32 v32, v32, v33
	v_cvt_pk_bf16_f32 v33, v34, v35
	v_cvt_pk_bf16_f32 v34, v24, v25
	v_cvt_pk_bf16_f32 v35, v26, v27
	global_store_dwordx4 v145, v[32:35], s[14:15] offset:256
	v_add_u32_e32 v145, 0x50000, v144
	v_cvt_pk_bf16_f32 v36, v36, v37
	v_cvt_pk_bf16_f32 v37, v38, v39
	v_cvt_pk_bf16_f32 v38, v28, v29
	v_cvt_pk_bf16_f32 v39, v30, v31
	global_store_dwordx4 v145, v[36:39], s[14:15]
	v_cvt_pk_bf16_f32 v16, v16, v17
	v_cvt_pk_bf16_f32 v17, v18, v19
	v_cvt_pk_bf16_f32 v18, v8, v9
	v_cvt_pk_bf16_f32 v19, v10, v11
	global_store_dwordx4 v145, v[16:19], s[14:15] offset:256
	v_add_u32_e32 v145, 0x58000, v144
	v_cvt_pk_bf16_f32 v20, v20, v21
	v_cvt_pk_bf16_f32 v21, v22, v23
	v_cvt_pk_bf16_f32 v22, v12, v13
	v_cvt_pk_bf16_f32 v23, v14, v15
	global_store_dwordx4 v145, v[20:23], s[14:15]
	v_cvt_pk_bf16_f32 v4, v4, v5
	v_cvt_pk_bf16_f32 v5, v6, v7
	v_cvt_pk_bf16_f32 v6, v0, v1
	v_cvt_pk_bf16_f32 v7, v2, v3
	global_store_dwordx4 v145, v[4:7], s[14:15] offset:256
	s_andn2_b64 vcc, exec, s[10:11]
	s_mov_b64 s[10:11], -1
	s_cbranch_vccnz .LBB0_1081
	s_andn2_b64 vcc, exec, s[6:7]
	s_cbranch_vccnz .LBB0_1080
	s_barrier
	s_branch .LBB0_1080

; #define PG8_STAGE(bufoff, gbase, voff, p64) do { _Pragma("unroll") for (int _i = 0; _i < 2; ++_i) { \
;         const char* _gb = (const char*)(gbase) + (size_t)_i * (p64); const unsigned _la = ldsbase + (unsigned)(bufoff) + (unsigned)_i * 8192u; \
;         asm volatile("s_mov_b32 m0, %0\n\ts_nop 0\n\tglobal_load_lds_dwordx4 %1, %2" :: "s"(_la), "v"(voff), "s"(_gb) : "memory"); } } while (0)
; #define PG8_LDA(dst, b, h) do { _Pragma("unroll") for (int m = 0; m < 4; ++m) _Pragma("unroll") for (int k = 0; k < 2; ++k) dst[m][k] = *(const LAS bf16x8*)(lds + PG8_SA(b, h) + aoff + m * 2048 + k * 1024); } while (0)
; #define PG8_LDB(dst, b, h) do { _Pragma("unroll") for (int n = 0; n < 2; ++n) _Pragma("unroll") for (int k = 0; k < 2; ++k) dst[n][k] = *(const LAS bf16x8*)(lds + PG8_SB(b, h) + boff + n * 2048 + k * 1024); } while (0)
; #define PG8_MMA(ai, bj, At, Bt) do { __builtin_amdgcn_s_setprio(1); _Pragma("unroll") for (int m = 0; m < 4; ++m) _Pragma("unroll") for (int n = 0; n < 2; ++n) _Pragma("unroll") for (int k = 0; k < 2; ++k) \
;         acc[ai][bj][m][n] = __builtin_amdgcn_mfma_f32_16x16x32_bf16(Bt[n][k], At[m][k], acc[ai][bj][m][n], 0, 0, 0); __builtin_amdgcn_s_setprio(0); } while (0)
; #define PG8_WAIT_V(n) asm volatile("s_waitcnt vmcnt(" #n ")" ::: "memory")
; #define PG8_WAIT_L(n) asm volatile("s_waitcnt lgkmcnt(" #n ")" ::: "memory")
; #define PG8_BAR __builtin_amdgcn_s_barrier()
; #define PG8_SCHED __builtin_amdgcn_sched_barrier(0)
; template <class Epi, class Sched>
; __device__ __forceinline__ void gemm_phase(LAS unsigned char* lds, const Sched& S, const Epi& E) {
;     ...
;             PG8_LDB(B0, 0, 0); PG8_LDB(B1, 0, 1); PG8_SCHED; PG8_LDA(At, 0, 0); PG8_STAGE(PG8_SA(1, 1), a1 + hA, voffA, hA / 2);
;             PG8_WAIT_V(8); PG8_WAIT_L(0); PG8_BAR; PG8_MMA(0, 0, At, B0); PG8_MMA(0, 1, At, B1); PG8_BAR; PG8_SCHED;
.LBB0_1191:
	s_add_u32 s24, s24, 0x40080
	s_addc_u32 s25, s25, 0
	s_add_u32 s58, s26, 0x100
	s_addc_u32 s59, s27, 0
	s_mov_b32 s60, -2
	ds_read_b128 v[144:147], v138
	ds_read_b128 v[148:151], v138 offset:1024
	ds_read_b128 v[152:155], v138 offset:2048
	ds_read_b128 v[156:159], v138 offset:3072
	ds_read_b128 v[160:163], v139
	ds_read_b128 v[164:167], v139 offset:1024
	ds_read_b128 v[168:171], v139 offset:2048
	ds_read_b128 v[172:175], v139 offset:3072
	s_add_u32 s26, s24, 0xfffc0080
	s_addc_u32 s27, s25, -1
	s_cmp_eq_u32 s60, 12
	s_cselect_b32 s26, s20, s26
	s_cselect_b32 s27, s21, s27
	s_cselect_b32 s40, s22, s58
	s_cselect_b32 s41, s23, s59
	s_add_u32 s38, s26, 0x80
	s_addc_u32 s39, s27, 0
	ds_read_b128 v[178:181], v140
	ds_read_b128 v[182:185], v140 offset:1024
	ds_read_b128 v[186:189], v140 offset:2048
	ds_read_b128 v[190:193], v140 offset:3072
	ds_read_b128 v[194:197], v140 offset:4096
	ds_read_b128 v[198:201], v140 offset:5120
	ds_read_b128 v[202:205], v140 offset:6144
	ds_read_b128 v[206:209], v140 offset:7168
	s_mov_b32 m0, s54
	s_nop 0
	global_load_lds_dwordx4 v134, s[24:25]
	s_add_u32 s62, s24, 0x20000
	s_mov_b32 m0, s55
	s_addc_u32 s63, s25, 0
	global_load_lds_dwordx4 v134, s[62:63]
	s_cmp_eq_u32 s19, 0
	s_cbranch_scc1 .Lpeel_strict_35719_1
	s_waitcnt vmcnt(24) lgkmcnt(0)
	s_branch .Lpeel_join_35719_1

; #define PG8_STAGE(bufoff, gbase, voff, p64) do { _Pragma("unroll") for (int _i = 0; _i < 2; ++_i) { \
;         const char* _gb = (const char*)(gbase) + (size_t)_i * (p64); const unsigned _la = ldsbase + (unsigned)(bufoff) + (unsigned)_i * 8192u; \
;         asm volatile("s_mov_b32 m0, %0\n\ts_nop 0\n\tglobal_load_lds_dwordx4 %1, %2" :: "s"(_la), "v"(voff), "s"(_gb) : "memory"); } } while (0)
; #define PG8_LDA(dst, b, h) do { _Pragma("unroll") for (int m = 0; m < 4; ++m) _Pragma("unroll") for (int k = 0; k < 2; ++k) dst[m][k] = *(const LAS bf16x8*)(lds + PG8_SA(b, h) + aoff + m * 2048 + k * 1024); } while (0)
; #define PG8_MMA(ai, bj, At, Bt) do { __builtin_amdgcn_s_setprio(1); _Pragma("unroll") for (int m = 0; m < 4; ++m) _Pragma("unroll") for (int n = 0; n < 2; ++n) _Pragma("unroll") for (int k = 0; k < 2; ++k) \
;         acc[ai][bj][m][n] = __builtin_amdgcn_mfma_f32_16x16x32_bf16(Bt[n][k], At[m][k], acc[ai][bj][m][n], 0, 0, 0); __builtin_amdgcn_s_setprio(0); } while (0)
; #define PG8_WAIT_V(n) asm volatile("s_waitcnt vmcnt(" #n ")" ::: "memory")
; #define PG8_WAIT_L(n) asm volatile("s_waitcnt lgkmcnt(" #n ")" ::: "memory")
; #define PG8_BAR __builtin_amdgcn_s_barrier()
; #define PG8_SCHED __builtin_amdgcn_sched_barrier(0)
; template <class Epi, class Sched>
; __device__ __forceinline__ void gemm_phase(LAS unsigned char* lds, const Sched& S, const Epi& E) {
;     ...
;             PG8_WAIT_V(8); PG8_WAIT_L(0); PG8_BAR; PG8_MMA(0, 0, At, B0); PG8_MMA(0, 1, At, B1); PG8_BAR; PG8_SCHED;
;             PG8_LDA(At, 0, 1); PG8_STAGE(PG8_SB(0, 0), b2, vB2, hB2 / 2); PG8_STAGE(PG8_SB(0, 1), b2 + hB2, vB2, hB2 / 2); PG8_STAGE(PG8_SA(0, 0), a2, vA2, hA2 / 2);
.Lpeel_join_35719_1:
	s_barrier
	v_mfma_f32_16x16x32_bf16 v[124:127], v[144:147], v[178:181], 0
	v_mfma_f32_16x16x32_bf16 v[120:123], v[152:155], v[178:181], 0
	v_mfma_f32_16x16x32_bf16 v[116:119], v[144:147], v[186:189], 0
	v_mfma_f32_16x16x32_bf16 v[108:111], v[152:155], v[186:189], 0
	v_mfma_f32_16x16x32_bf16 v[100:103], v[144:147], v[194:197], 0
	v_mfma_f32_16x16x32_bf16 v[92:95], v[152:155], v[194:197], 0
	v_mfma_f32_16x16x32_bf16 v[84:87], v[144:147], v[202:205], 0
	v_mfma_f32_16x16x32_bf16 v[76:79], v[152:155], v[202:205], 0
	v_mfma_f32_16x16x32_bf16 v[124:127], v[148:151], v[182:185], v[124:127]
	v_mfma_f32_16x16x32_bf16 v[120:123], v[156:159], v[182:185], v[120:123]
	v_mfma_f32_16x16x32_bf16 v[116:119], v[148:151], v[190:193], v[116:119]
	v_mfma_f32_16x16x32_bf16 v[108:111], v[156:159], v[190:193], v[108:111]
	v_mfma_f32_16x16x32_bf16 v[100:103], v[148:151], v[198:201], v[100:103]
	v_mfma_f32_16x16x32_bf16 v[92:95], v[156:159], v[198:201], v[92:95]
	v_mfma_f32_16x16x32_bf16 v[84:87], v[148:151], v[206:209], v[84:87]
	v_mfma_f32_16x16x32_bf16 v[76:79], v[156:159], v[206:209], v[76:79]
	v_mfma_f32_16x16x32_bf16 v[112:115], v[160:163], v[178:181], 0
	v_mfma_f32_16x16x32_bf16 v[104:107], v[168:171], v[178:181], 0
	v_mfma_f32_16x16x32_bf16 v[96:99], v[160:163], v[186:189], 0
	v_mfma_f32_16x16x32_bf16 v[88:91], v[168:171], v[186:189], 0
	v_mfma_f32_16x16x32_bf16 v[80:83], v[160:163], v[194:197], 0
	v_mfma_f32_16x16x32_bf16 v[72:75], v[168:171], v[194:197], 0
	v_mfma_f32_16x16x32_bf16 v[68:71], v[160:163], v[202:205], 0
	v_mfma_f32_16x16x32_bf16 v[64:67], v[168:171], v[202:205], 0
	v_mfma_f32_16x16x32_bf16 v[112:115], v[164:167], v[182:185], v[112:115]
	v_mfma_f32_16x16x32_bf16 v[104:107], v[172:175], v[182:185], v[104:107]
	v_mfma_f32_16x16x32_bf16 v[96:99], v[164:167], v[190:193], v[96:99]
	v_mfma_f32_16x16x32_bf16 v[88:91], v[172:175], v[190:193], v[88:91]
	v_mfma_f32_16x16x32_bf16 v[80:83], v[164:167], v[198:201], v[80:83]
	v_mfma_f32_16x16x32_bf16 v[72:75], v[172:175], v[198:201], v[72:75]
	v_mfma_f32_16x16x32_bf16 v[68:71], v[164:167], v[206:209], v[68:71]
	v_mfma_f32_16x16x32_bf16 v[64:67], v[172:175], v[206:209], v[64:67]
	s_add_i32 s60, s60, 2
	s_add_u32 s24, s24, 0x100
	s_addc_u32 s25, s25, 0
	s_add_u32 s58, s58, 0x100
	s_addc_u32 s59, s59, 0
	s_barrier
	s_add_u32 s62, s40, 0x20000
	ds_read_b128 v[178:181], v140 offset:16384
	ds_read_b128 v[182:185], v140 offset:17408
	ds_read_b128 v[186:189], v140 offset:18432
	ds_read_b128 v[190:193], v140 offset:19456
	ds_read_b128 v[194:197], v140 offset:20480
	ds_read_b128 v[198:201], v140 offset:21504
	ds_read_b128 v[202:205], v140 offset:22528
	ds_read_b128 v[206:209], v140 offset:23552
	s_mov_b32 m0, s35
	s_nop 0
	global_load_lds_dwordx4 v135, s[40:41]
	s_mov_b32 m0, s36
	s_addc_u32 s63, s41, 0
	global_load_lds_dwordx4 v135, s[62:63]
	s_add_u32 s62, s40, 0x40000
	s_mov_b32 m0, s37
	s_addc_u32 s63, s41, 0
	global_load_lds_dwordx4 v135, s[62:63]
	s_add_u32 s62, s40, 0x60000
	s_mov_b32 m0, s42
	s_addc_u32 s63, s41, 0
	global_load_lds_dwordx4 v135, s[62:63]
	s_mov_b32 m0, s34
	s_nop 0
	global_load_lds_dwordx4 v134, s[26:27]
	s_add_u32 s62, s26, 0x20000
	s_mov_b32 m0, s43
	s_addc_u32 s63, s27, 0
	global_load_lds_dwordx4 v134, s[62:63]
	s_cmp_eq_u32 s19, 0
	s_cbranch_scc1 .Lpeel_strict_35719_0
	s_waitcnt vmcnt(24) lgkmcnt(0)
	s_branch .Lpeel_join_35719_0

; __device__ __forceinline__ u32x4 pack8(const f32x4 a, const f32x4 b) { u32x4 w; w.x = pk2(a[0], a[1]); w.y = pk2(a[2], a[3]); w.z = pk2(b[0], b[1]); w.w = pk2(b[2], b[3]); return w; }
;     __device__ __forceinline__ bool operator()(EPI_ARGS) const {
; #pragma unroll
;         for (int ai = 0; ai < 2; ++ai)
; #pragma unroll
;             for (int m = 0; m < 4; ++m) {
;                 const size_t row = (size_t)u.pm * 256 + ROWLOC(ai, m);
; #pragma unroll
;                 for (int bj = 0; bj < 2; ++bj) *(u32x4*)(dst + row * ld + u.pn * 256 + COLLOC(bj)) = pack8(acc[ai][bj][m][0], acc[ai][bj][m][1]);
;             }
.LBB0_1201:
	s_lshl_b32 s24, s18, 19
	s_lshl_b32 s26, s57, 9
	s_add_i32 s24, s24, s26
	s_lshl_b32 s26, s47, 1
	s_add_i32 s24, s24, s26
	v_add_u32_e32 v144, s46, v136
	v_lshlrev_b32_e32 v145, 4, v137
	v_lshl_add_u32 v144, v144, 11, v145
	v_add_u32_e32 v144, s24, v144
	v_cvt_pk_bf16_f32 v124, v124, v125
	v_cvt_pk_bf16_f32 v125, v126, v127
	v_cvt_pk_bf16_f32 v126, v120, v121
	v_cvt_pk_bf16_f32 v127, v122, v123
	global_store_dwordx4 v144, v[124:127], s[12:13]
	v_cvt_pk_bf16_f32 v112, v112, v113
	v_cvt_pk_bf16_f32 v113, v114, v115
	v_cvt_pk_bf16_f32 v114, v104, v105
	v_cvt_pk_bf16_f32 v115, v106, v107
	global_store_dwordx4 v144, v[112:115], s[12:13] offset:256
	v_add_u32_e32 v145, 0x8000, v144
	v_cvt_pk_bf16_f32 v116, v116, v117
	v_cvt_pk_bf16_f32 v117, v118, v119
	v_cvt_pk_bf16_f32 v118, v108, v109
	v_cvt_pk_bf16_f32 v119, v110, v111
	global_store_dwordx4 v145, v[116:119], s[12:13]
	v_cvt_pk_bf16_f32 v96, v96, v97
	v_cvt_pk_bf16_f32 v97, v98, v99
	v_cvt_pk_bf16_f32 v98, v88, v89
	v_cvt_pk_bf16_f32 v99, v90, v91
	global_store_dwordx4 v145, v[96:99], s[12:13] offset:256
	v_add_u32_e32 v145, 0x10000, v144
	v_cvt_pk_bf16_f32 v100, v100, v101
	v_cvt_pk_bf16_f32 v101, v102, v103
	v_cvt_pk_bf16_f32 v102, v92, v93
	v_cvt_pk_bf16_f32 v103, v94, v95
	global_store_dwordx4 v145, v[100:103], s[12:13]
	v_cvt_pk_bf16_f32 v80, v80, v81
	v_cvt_pk_bf16_f32 v81, v82, v83
	v_cvt_pk_bf16_f32 v82, v72, v73
	v_cvt_pk_bf16_f32 v83, v74, v75
	global_store_dwordx4 v145, v[80:83], s[12:13] offset:256
	v_add_u32_e32 v145, 0x18000, v144
	v_cvt_pk_bf16_f32 v84, v84, v85
	v_cvt_pk_bf16_f32 v85, v86, v87
	v_cvt_pk_bf16_f32 v86, v76, v77
	v_cvt_pk_bf16_f32 v87, v78, v79
	global_store_dwordx4 v145, v[84:87], s[12:13]
	v_cvt_pk_bf16_f32 v68, v68, v69
	v_cvt_pk_bf16_f32 v69, v70, v71
	v_cvt_pk_bf16_f32 v70, v64, v65
	v_cvt_pk_bf16_f32 v71, v66, v67
	global_store_dwordx4 v145, v[68:71], s[12:13] offset:256
	v_add_u32_e32 v145, 0x40000, v144
	v_cvt_pk_bf16_f32 v60, v60, v61
	v_cvt_pk_bf16_f32 v61, v62, v63
	v_cvt_pk_bf16_f32 v62, v56, v57
	v_cvt_pk_bf16_f32 v63, v58, v59
	global_store_dwordx4 v145, v[60:63], s[12:13]
	v_cvt_pk_bf16_f32 v48, v48, v49
	v_cvt_pk_bf16_f32 v49, v50, v51
	v_cvt_pk_bf16_f32 v50, v40, v41
	v_cvt_pk_bf16_f32 v51, v42, v43
	global_store_dwordx4 v145, v[48:51], s[12:13] offset:256
	v_add_u32_e32 v145, 0x48000, v144
	v_cvt_pk_bf16_f32 v52, v52, v53
	v_cvt_pk_bf16_f32 v53, v54, v55
	v_cvt_pk_bf16_f32 v54, v44, v45
	v_cvt_pk_bf16_f32 v55, v46, v47
	global_store_dwordx4 v145, v[52:55], s[12:13]
	v_cvt_pk_bf16_f32 v32, v32, v33
	v_cvt_pk_bf16_f32 v33, v34, v35
	v_cvt_pk_bf16_f32 v34, v24, v25
	v_cvt_pk_bf16_f32 v35, v26, v27
	global_store_dwordx4 v145, v[32:35], s[12:13] offset:256
	v_add_u32_e32 v145, 0x50000, v144
	v_cvt_pk_bf16_f32 v36, v36, v37
	v_cvt_pk_bf16_f32 v37, v38, v39
	v_cvt_pk_bf16_f32 v38, v28, v29
	v_cvt_pk_bf16_f32 v39, v30, v31
	global_store_dwordx4 v145, v[36:39], s[12:13]
	v_cvt_pk_bf16_f32 v16, v16, v17
	v_cvt_pk_bf16_f32 v17, v18, v19
	v_cvt_pk_bf16_f32 v18, v8, v9
	v_cvt_pk_bf16_f32 v19, v10, v11
	global_store_dwordx4 v145, v[16:19], s[12:13] offset:256
	v_add_u32_e32 v145, 0x58000, v144
	v_cvt_pk_bf16_f32 v20, v20, v21
	v_cvt_pk_bf16_f32 v21, v22, v23
	v_cvt_pk_bf16_f32 v22, v12, v13
	v_cvt_pk_bf16_f32 v23, v14, v15
	global_store_dwordx4 v145, v[20:23], s[12:13]
	v_cvt_pk_bf16_f32 v4, v4, v5
	v_cvt_pk_bf16_f32 v5, v6, v7
	v_cvt_pk_bf16_f32 v6, v0, v1
	v_cvt_pk_bf16_f32 v7, v2, v3
	global_store_dwordx4 v145, v[4:7], s[12:13] offset:256
	s_andn2_b64 vcc, exec, s[10:11]
	s_mov_b64 s[10:11], -1
	s_cbranch_vccnz .LBB0_1184
	s_andn2_b64 vcc, exec, s[6:7]
	s_cbranch_vccnz .LBB0_1183
	s_barrier
	s_branch .LBB0_1183

; #define PG8_STAGE(bufoff, gbase, voff, p64) do { _Pragma("unroll") for (int _i = 0; _i < 2; ++_i) { \
;         const char* _gb = (const char*)(gbase) + (size_t)_i * (p64); const unsigned _la = ldsbase + (unsigned)(bufoff) + (unsigned)_i * 8192u; \
;         asm volatile("s_mov_b32 m0, %0\n\ts_nop 0\n\tglobal_load_lds_dwordx4 %1, %2" :: "s"(_la), "v"(voff), "s"(_gb) : "memory"); } } while (0)
; #define PG8_LDA(dst, b, h) do { _Pragma("unroll") for (int m = 0; m < 4; ++m) _Pragma("unroll") for (int k = 0; k < 2; ++k) dst[m][k] = *(const LAS bf16x8*)(lds + PG8_SA(b, h) + aoff + m * 2048 + k * 1024); } while (0)
; #define PG8_LDB(dst, b, h) do { _Pragma("unroll") for (int n = 0; n < 2; ++n) _Pragma("unroll") for (int k = 0; k < 2; ++k) dst[n][k] = *(const LAS bf16x8*)(lds + PG8_SB(b, h) + boff + n * 2048 + k * 1024); } while (0)
; #define PG8_MMA(ai, bj, At, Bt) do { __builtin_amdgcn_s_setprio(1); _Pragma("unroll") for (int m = 0; m < 4; ++m) _Pragma("unroll") for (int n = 0; n < 2; ++n) _Pragma("unroll") for (int k = 0; k < 2; ++k) \
;         acc[ai][bj][m][n] = __builtin_amdgcn_mfma_f32_16x16x32_bf16(Bt[n][k], At[m][k], acc[ai][bj][m][n], 0, 0, 0); __builtin_amdgcn_s_setprio(0); } while (0)
; #define PG8_WAIT_V(n) asm volatile("s_waitcnt vmcnt(" #n ")" ::: "memory")
; #define PG8_WAIT_L(n) asm volatile("s_waitcnt lgkmcnt(" #n ")" ::: "memory")
; #define PG8_BAR __builtin_amdgcn_s_barrier()
; #define PG8_SCHED __builtin_amdgcn_sched_barrier(0)
; template <class Epi, class Sched>
; __device__ __forceinline__ void gemm_phase(LAS unsigned char* lds, const Sched& S, const Epi& E) {
;     ...
;             PG8_LDB(B0, 0, 0); PG8_LDB(B1, 0, 1); PG8_SCHED; PG8_LDA(At, 0, 0); PG8_STAGE(PG8_SA(1, 1), a1 + hA, voffA, hA / 2);
;             PG8_WAIT_V(8); PG8_WAIT_L(0); PG8_BAR; PG8_MMA(0, 0, At, B0); PG8_MMA(0, 1, At, B1); PG8_BAR; PG8_SCHED;
.LBB0_1273:
	s_add_u32 s38, s38, 0x40080
	s_addc_u32 s39, s39, 0
	s_add_u32 s61, s40, 0x100
	s_addc_u32 s62, s41, 0
	s_mov_b32 s63, -2
	s_waitcnt vmcnt(3)
	s_waitcnt vmcnt(1)
	s_waitcnt vmcnt(0)
	ds_read_b128 v[128:131], v156
	ds_read_b128 v[132:135], v156 offset:1024
	ds_read_b128 v[140:143], v156 offset:2048
	ds_read_b128 v[144:147], v156 offset:3072
	ds_read_b128 v[148:151], v157
	ds_read_b128 v[162:165], v157 offset:1024
	ds_read_b128 v[166:169], v157 offset:2048
	ds_read_b128 v[170:173], v157 offset:3072
	s_add_u32 s30, s38, 0xfffc0080
	s_addc_u32 s40, s39, -1
	s_cmp_eq_u32 s63, 12
	s_cselect_b32 s41, s25, s40
	s_cselect_b32 s40, s24, s30
	s_cselect_b32 s44, s26, s61
	s_cselect_b32 s45, s27, s62
	s_add_u32 s42, s40, 0x80
	s_addc_u32 s43, s41, 0
	ds_read_b128 v[178:181], v158
	ds_read_b128 v[182:185], v158 offset:1024
	ds_read_b128 v[186:189], v158 offset:2048
	ds_read_b128 v[190:193], v158 offset:3072
	ds_read_b128 v[194:197], v158 offset:4096
	ds_read_b128 v[198:201], v158 offset:5120
	ds_read_b128 v[202:205], v158 offset:6144
	ds_read_b128 v[206:209], v158 offset:7168
	s_mov_b32 m0, s57
	s_nop 0
	global_load_lds_dwordx4 v152, s[38:39]
	s_add_u32 s66, s38, 0x20000
	s_mov_b32 m0, s58
	s_addc_u32 s67, s39, 0
	global_load_lds_dwordx4 v152, s[66:67]
	s_cmp_eq_u32 s23, 0
	s_cbranch_scc1 .Lpeel_strict_37227_1
	s_waitcnt vmcnt(16) lgkmcnt(0)
	s_branch .Lpeel_join_37227_1

; #define PG8_STAGE(bufoff, gbase, voff, p64) do { _Pragma("unroll") for (int _i = 0; _i < 2; ++_i) { \
;         const char* _gb = (const char*)(gbase) + (size_t)_i * (p64); const unsigned _la = ldsbase + (unsigned)(bufoff) + (unsigned)_i * 8192u; \
;         asm volatile("s_mov_b32 m0, %0\n\ts_nop 0\n\tglobal_load_lds_dwordx4 %1, %2" :: "s"(_la), "v"(voff), "s"(_gb) : "memory"); } } while (0)
; #define PG8_LDA(dst, b, h) do { _Pragma("unroll") for (int m = 0; m < 4; ++m) _Pragma("unroll") for (int k = 0; k < 2; ++k) dst[m][k] = *(const LAS bf16x8*)(lds + PG8_SA(b, h) + aoff + m * 2048 + k * 1024); } while (0)
; #define PG8_MMA(ai, bj, At, Bt) do { __builtin_amdgcn_s_setprio(1); _Pragma("unroll") for (int m = 0; m < 4; ++m) _Pragma("unroll") for (int n = 0; n < 2; ++n) _Pragma("unroll") for (int k = 0; k < 2; ++k) \
;         acc[ai][bj][m][n] = __builtin_amdgcn_mfma_f32_16x16x32_bf16(Bt[n][k], At[m][k], acc[ai][bj][m][n], 0, 0, 0); __builtin_amdgcn_s_setprio(0); } while (0)
; #define PG8_WAIT_V(n) asm volatile("s_waitcnt vmcnt(" #n ")" ::: "memory")
; #define PG8_WAIT_L(n) asm volatile("s_waitcnt lgkmcnt(" #n ")" ::: "memory")
; #define PG8_BAR __builtin_amdgcn_s_barrier()
; #define PG8_SCHED __builtin_amdgcn_sched_barrier(0)
; template <class Epi, class Sched>
; __device__ __forceinline__ void gemm_phase(LAS unsigned char* lds, const Sched& S, const Epi& E) {
;     ...
;             PG8_WAIT_V(8); PG8_WAIT_L(0); PG8_BAR; PG8_MMA(0, 0, At, B0); PG8_MMA(0, 1, At, B1); PG8_BAR; PG8_SCHED;
;             PG8_LDA(At, 0, 1); PG8_STAGE(PG8_SB(0, 0), b2, vB2, hB2 / 2); PG8_STAGE(PG8_SB(0, 1), b2 + hB2, vB2, hB2 / 2); PG8_STAGE(PG8_SA(0, 0), a2, vA2, hA2 / 2);
.Lpeel_join_37227_1:
	s_barrier
	v_mfma_f32_16x16x32_bf16 v[124:127], v[128:131], v[178:181], 0
	v_mfma_f32_16x16x32_bf16 v[116:119], v[140:143], v[178:181], 0
	v_mfma_f32_16x16x32_bf16 v[108:111], v[128:131], v[186:189], 0
	v_mfma_f32_16x16x32_bf16 v[100:103], v[140:143], v[186:189], 0
	v_mfma_f32_16x16x32_bf16 v[92:95], v[128:131], v[194:197], 0
	v_mfma_f32_16x16x32_bf16 v[84:87], v[140:143], v[194:197], 0
	v_mfma_f32_16x16x32_bf16 v[76:79], v[128:131], v[202:205], 0
	v_mfma_f32_16x16x32_bf16 v[68:71], v[140:143], v[202:205], 0
	v_mfma_f32_16x16x32_bf16 v[124:127], v[132:135], v[182:185], v[124:127]
	v_mfma_f32_16x16x32_bf16 v[116:119], v[144:147], v[182:185], v[116:119]
	v_mfma_f32_16x16x32_bf16 v[108:111], v[132:135], v[190:193], v[108:111]
	v_mfma_f32_16x16x32_bf16 v[100:103], v[144:147], v[190:193], v[100:103]
	v_mfma_f32_16x16x32_bf16 v[92:95], v[132:135], v[198:201], v[92:95]
	v_mfma_f32_16x16x32_bf16 v[84:87], v[144:147], v[198:201], v[84:87]
	v_mfma_f32_16x16x32_bf16 v[76:79], v[132:135], v[206:209], v[76:79]
	v_mfma_f32_16x16x32_bf16 v[68:71], v[144:147], v[206:209], v[68:71]
	v_mfma_f32_16x16x32_bf16 v[120:123], v[148:151], v[178:181], 0
	v_mfma_f32_16x16x32_bf16 v[112:115], v[166:169], v[178:181], 0
	v_mfma_f32_16x16x32_bf16 v[104:107], v[148:151], v[186:189], 0
	v_mfma_f32_16x16x32_bf16 v[96:99], v[166:169], v[186:189], 0
	v_mfma_f32_16x16x32_bf16 v[88:91], v[148:151], v[194:197], 0
	v_mfma_f32_16x16x32_bf16 v[80:83], v[166:169], v[194:197], 0
	v_mfma_f32_16x16x32_bf16 v[72:75], v[148:151], v[202:205], 0
	v_mfma_f32_16x16x32_bf16 v[64:67], v[166:169], v[202:205], 0
	v_mfma_f32_16x16x32_bf16 v[120:123], v[162:165], v[182:185], v[120:123]
	v_mfma_f32_16x16x32_bf16 v[112:115], v[170:173], v[182:185], v[112:115]
	v_mfma_f32_16x16x32_bf16 v[104:107], v[162:165], v[190:193], v[104:107]
	v_mfma_f32_16x16x32_bf16 v[96:99], v[170:173], v[190:193], v[96:99]
	v_mfma_f32_16x16x32_bf16 v[88:91], v[162:165], v[198:201], v[88:91]
	v_mfma_f32_16x16x32_bf16 v[80:83], v[170:173], v[198:201], v[80:83]
	v_mfma_f32_16x16x32_bf16 v[72:75], v[162:165], v[206:209], v[72:75]
	v_mfma_f32_16x16x32_bf16 v[64:67], v[170:173], v[206:209], v[64:67]
	s_add_i32 s63, s63, 2
	s_add_u32 s38, s38, 0x100
	s_addc_u32 s39, s39, 0
	s_add_u32 s61, s61, 0x100
	s_addc_u32 s62, s62, 0
	s_barrier
	s_add_u32 s66, s44, 0x20000
	ds_read_b128 v[178:181], v158 offset:16384
	ds_read_b128 v[182:185], v158 offset:17408
	ds_read_b128 v[186:189], v158 offset:18432
	ds_read_b128 v[190:193], v158 offset:19456
	ds_read_b128 v[194:197], v158 offset:20480
	ds_read_b128 v[198:201], v158 offset:21504
	ds_read_b128 v[202:205], v158 offset:22528
	ds_read_b128 v[206:209], v158 offset:23552
	s_mov_b32 m0, s35
	s_nop 0
	global_load_lds_dwordx4 v153, s[44:45]
	s_mov_b32 m0, s36
	s_addc_u32 s67, s45, 0
	global_load_lds_dwordx4 v153, s[66:67]
	s_add_u32 s66, s44, 0x40000
	s_mov_b32 m0, s37
	s_addc_u32 s67, s45, 0
	global_load_lds_dwordx4 v153, s[66:67]
	s_add_u32 s66, s44, 0x60000
	s_mov_b32 m0, s46
	s_addc_u32 s67, s45, 0
	global_load_lds_dwordx4 v153, s[66:67]
	s_mov_b32 m0, s34
	s_nop 0
	global_load_lds_dwordx4 v152, s[40:41]
	s_add_u32 s66, s40, 0x20000
	s_mov_b32 m0, s47
	s_addc_u32 s67, s41, 0
	global_load_lds_dwordx4 v152, s[66:67]
	s_cmp_eq_u32 s23, 0
	s_cbranch_scc1 .Lpeel_strict_37227_0
	s_waitcnt vmcnt(16) lgkmcnt(0)
	s_branch .Lpeel_join_37227_0

; #define PG8_MMA(ai, bj, At, Bt) do { __builtin_amdgcn_s_setprio(1); _Pragma("unroll") for (int m = 0; m < 4; ++m) _Pragma("unroll") for (int n = 0; n < 2; ++n) _Pragma("unroll") for (int k = 0; k < 2; ++k) \
;         acc[ai][bj][m][n] = __builtin_amdgcn_mfma_f32_16x16x32_bf16(Bt[n][k], At[m][k], acc[ai][bj][m][n], 0, 0, 0); __builtin_amdgcn_s_setprio(0); } while (0)
; #define PG8_WAIT_V(n) asm volatile("s_waitcnt vmcnt(" #n ")" ::: "memory")
; #define PG8_WAIT_L(n) asm volatile("s_waitcnt lgkmcnt(" #n ")" ::: "memory")
; #define PG8_BAR __builtin_amdgcn_s_barrier()
; #define PG8_SCHED __builtin_amdgcn_sched_barrier(0)
; template <class Epi, class Sched>
; __device__ __forceinline__ void gemm_phase(LAS unsigned char* lds, const Sched& S, const Epi& E) {
;     ...
;             PG8_WAIT_V(8); PG8_WAIT_L(0); PG8_BAR; PG8_MMA(1, 0, At, B0); PG8_MMA(1, 1, At, B1); PG8_BAR; PG8_SCHED;
.Lpeel_join_37227_0:
	s_barrier
	v_mfma_f32_16x16x32_bf16 v[60:63], v[128:131], v[178:181], 0
	v_mfma_f32_16x16x32_bf16 v[52:55], v[140:143], v[178:181], 0
	v_mfma_f32_16x16x32_bf16 v[44:47], v[128:131], v[186:189], 0
	v_mfma_f32_16x16x32_bf16 v[36:39], v[140:143], v[186:189], 0
	v_mfma_f32_16x16x32_bf16 v[28:31], v[128:131], v[194:197], 0
	v_mfma_f32_16x16x32_bf16 v[20:23], v[140:143], v[194:197], 0
	v_mfma_f32_16x16x32_bf16 v[12:15], v[128:131], v[202:205], 0
	v_mfma_f32_16x16x32_bf16 v[4:7], v[140:143], v[202:205], 0
	v_mfma_f32_16x16x32_bf16 v[60:63], v[132:135], v[182:185], v[60:63]
	v_mfma_f32_16x16x32_bf16 v[52:55], v[144:147], v[182:185], v[52:55]
	v_mfma_f32_16x16x32_bf16 v[44:47], v[132:135], v[190:193], v[44:47]
	v_mfma_f32_16x16x32_bf16 v[36:39], v[144:147], v[190:193], v[36:39]
	v_mfma_f32_16x16x32_bf16 v[28:31], v[132:135], v[198:201], v[28:31]
	v_mfma_f32_16x16x32_bf16 v[20:23], v[144:147], v[198:201], v[20:23]
	v_mfma_f32_16x16x32_bf16 v[12:15], v[132:135], v[206:209], v[12:15]
	v_mfma_f32_16x16x32_bf16 v[4:7], v[144:147], v[206:209], v[4:7]
	v_mfma_f32_16x16x32_bf16 v[56:59], v[148:151], v[178:181], 0
	v_mfma_f32_16x16x32_bf16 v[48:51], v[166:169], v[178:181], 0
	v_mfma_f32_16x16x32_bf16 v[40:43], v[148:151], v[186:189], 0
	v_mfma_f32_16x16x32_bf16 v[32:35], v[166:169], v[186:189], 0
	v_mfma_f32_16x16x32_bf16 v[24:27], v[148:151], v[194:197], 0
	v_mfma_f32_16x16x32_bf16 v[16:19], v[166:169], v[194:197], 0
	v_mfma_f32_16x16x32_bf16 v[8:11], v[148:151], v[202:205], 0
	v_mfma_f32_16x16x32_bf16 v[0:3], v[166:169], v[202:205], 0
	v_mfma_f32_16x16x32_bf16 v[56:59], v[162:165], v[182:185], v[56:59]
	v_mfma_f32_16x16x32_bf16 v[48:51], v[170:173], v[182:185], v[48:51]
	v_mfma_f32_16x16x32_bf16 v[40:43], v[162:165], v[190:193], v[40:43]
	v_mfma_f32_16x16x32_bf16 v[32:35], v[170:173], v[190:193], v[32:35]
	v_mfma_f32_16x16x32_bf16 v[24:27], v[162:165], v[198:201], v[24:27]
	v_mfma_f32_16x16x32_bf16 v[16:19], v[170:173], v[198:201], v[16:19]
	v_mfma_f32_16x16x32_bf16 v[8:11], v[162:165], v[206:209], v[8:11]
	v_mfma_f32_16x16x32_bf16 v[0:3], v[170:173], v[206:209], v[0:3]
	s_barrier
	s_branch .Lpeel_mid_37227

; #define PG8_STAGE(bufoff, gbase, voff, p64) do { _Pragma("unroll") for (int _i = 0; _i < 2; ++_i) { \
;         const char* _gb = (const char*)(gbase) + (size_t)_i * (p64); const unsigned _la = ldsbase + (unsigned)(bufoff) + (unsigned)_i * 8192u; \
;         asm volatile("s_mov_b32 m0, %0\n\ts_nop 0\n\tglobal_load_lds_dwordx4 %1, %2" :: "s"(_la), "v"(voff), "s"(_gb) : "memory"); } } while (0)
; #define PG8_LDA(dst, b, h) do { _Pragma("unroll") for (int m = 0; m < 4; ++m) _Pragma("unroll") for (int k = 0; k < 2; ++k) dst[m][k] = *(const LAS bf16x8*)(lds + PG8_SA(b, h) + aoff + m * 2048 + k * 1024); } while (0)
; #define PG8_LDB(dst, b, h) do { _Pragma("unroll") for (int n = 0; n < 2; ++n) _Pragma("unroll") for (int k = 0; k < 2; ++k) dst[n][k] = *(const LAS bf16x8*)(lds + PG8_SB(b, h) + boff + n * 2048 + k * 1024); } while (0)
; #define PG8_MMA(ai, bj, At, Bt) do { __builtin_amdgcn_s_setprio(1); _Pragma("unroll") for (int m = 0; m < 4; ++m) _Pragma("unroll") for (int n = 0; n < 2; ++n) _Pragma("unroll") for (int k = 0; k < 2; ++k) \
;         acc[ai][bj][m][n] = __builtin_amdgcn_mfma_f32_16x16x32_bf16(Bt[n][k], At[m][k], acc[ai][bj][m][n], 0, 0, 0); __builtin_amdgcn_s_setprio(0); } while (0)
; #define PG8_WAIT_V(n) asm volatile("s_waitcnt vmcnt(" #n ")" ::: "memory")
; #define PG8_WAIT_L(n) asm volatile("s_waitcnt lgkmcnt(" #n ")" ::: "memory")
; #define PG8_BAR __builtin_amdgcn_s_barrier()
; #define PG8_SCHED __builtin_amdgcn_sched_barrier(0)
; template <class Epi, class Sched>
; __device__ __forceinline__ void gemm_phase(LAS unsigned char* lds, const Sched& S, const Epi& E) {
;     ...
;             PG8_LDB(B0, 0, 0); PG8_LDB(B1, 0, 1); PG8_SCHED; PG8_LDA(At, 0, 0); PG8_STAGE(PG8_SA(1, 1), a1 + hA, voffA, hA / 2);
;             PG8_WAIT_V(8); PG8_WAIT_L(0); PG8_BAR; PG8_MMA(0, 0, At, B0); PG8_MMA(0, 1, At, B1); PG8_BAR; PG8_SCHED;
.LBB0_1351:
	s_add_u32 s22, s22, 0x40080
	s_addc_u32 s23, s23, 0
	s_add_u32 s59, s24, 0x100
	s_addc_u32 s60, s25, 0
	s_mov_b32 s61, -2
	s_waitcnt vmcnt(3)
	s_waitcnt vmcnt(2)
	s_waitcnt vmcnt(1)
	s_waitcnt vmcnt(0)
	ds_read_b128 v[128:131], v174
	ds_read_b128 v[132:135], v174 offset:1024
	ds_read_b128 v[136:139], v174 offset:2048
	ds_read_b128 v[144:147], v174 offset:3072
	ds_read_b128 v[148:151], v175
	ds_read_b128 v[152:155], v175 offset:1024
	ds_read_b128 v[156:159], v175 offset:2048
	ds_read_b128 v[160:163], v175 offset:3072
	s_add_u32 s24, s22, 0xfffc0080
	s_addc_u32 s25, s23, -1
	s_cmp_eq_u32 s61, 12
	s_cselect_b32 s24, s18, s24
	s_cselect_b32 s25, s19, s25
	s_cselect_b32 s38, s20, s59
	s_cselect_b32 s39, s21, s60
	s_add_u32 s26, s24, 0x80
	s_addc_u32 s27, s25, 0
	ds_read_b128 v[164:167], v177
	ds_read_b128 v[180:183], v177 offset:1024
	ds_read_b128 v[184:187], v177 offset:2048
	ds_read_b128 v[188:191], v177 offset:3072
	ds_read_b128 v[192:195], v177 offset:4096
	ds_read_b128 v[196:199], v177 offset:5120
	ds_read_b128 v[200:203], v177 offset:6144
	ds_read_b128 v[204:207], v177 offset:7168
	s_mov_b32 m0, s54
	s_nop 0
	global_load_lds_dwordx4 v170, s[22:23]
	s_add_u32 s62, s22, 0x20000
	s_mov_b32 m0, s55
	s_addc_u32 s63, s23, 0
	global_load_lds_dwordx4 v170, s[62:63]
	s_cmp_eq_u32 s17, 0
	s_cbranch_scc1 .Lpeel_strict_39287_1
	s_waitcnt vmcnt(24) lgkmcnt(0)
	s_branch .Lpeel_join_39287_1

; #define PG8_STAGE(bufoff, gbase, voff, p64) do { _Pragma("unroll") for (int _i = 0; _i < 2; ++_i) { \
;         const char* _gb = (const char*)(gbase) + (size_t)_i * (p64); const unsigned _la = ldsbase + (unsigned)(bufoff) + (unsigned)_i * 8192u; \
;         asm volatile("s_mov_b32 m0, %0\n\ts_nop 0\n\tglobal_load_lds_dwordx4 %1, %2" :: "s"(_la), "v"(voff), "s"(_gb) : "memory"); } } while (0)
; #define PG8_LDA(dst, b, h) do { _Pragma("unroll") for (int m = 0; m < 4; ++m) _Pragma("unroll") for (int k = 0; k < 2; ++k) dst[m][k] = *(const LAS bf16x8*)(lds + PG8_SA(b, h) + aoff + m * 2048 + k * 1024); } while (0)
; #define PG8_MMA(ai, bj, At, Bt) do { __builtin_amdgcn_s_setprio(1); _Pragma("unroll") for (int m = 0; m < 4; ++m) _Pragma("unroll") for (int n = 0; n < 2; ++n) _Pragma("unroll") for (int k = 0; k < 2; ++k) \
;         acc[ai][bj][m][n] = __builtin_amdgcn_mfma_f32_16x16x32_bf16(Bt[n][k], At[m][k], acc[ai][bj][m][n], 0, 0, 0); __builtin_amdgcn_s_setprio(0); } while (0)
; #define PG8_WAIT_V(n) asm volatile("s_waitcnt vmcnt(" #n ")" ::: "memory")
; #define PG8_WAIT_L(n) asm volatile("s_waitcnt lgkmcnt(" #n ")" ::: "memory")
; #define PG8_BAR __builtin_amdgcn_s_barrier()
; #define PG8_SCHED __builtin_amdgcn_sched_barrier(0)
; template <class Epi, class Sched>
; __device__ __forceinline__ void gemm_phase(LAS unsigned char* lds, const Sched& S, const Epi& E) {
;     ...
;             PG8_WAIT_V(8); PG8_WAIT_L(0); PG8_BAR; PG8_MMA(0, 0, At, B0); PG8_MMA(0, 1, At, B1); PG8_BAR; PG8_SCHED;
;             PG8_LDA(At, 0, 1); PG8_STAGE(PG8_SB(0, 0), b2, vB2, hB2 / 2); PG8_STAGE(PG8_SB(0, 1), b2 + hB2, vB2, hB2 / 2); PG8_STAGE(PG8_SA(0, 0), a2, vA2, hA2 / 2);
.Lpeel_join_39287_1:
	s_barrier
	v_mfma_f32_16x16x32_bf16 v[84:87], v[128:131], v[164:167], 0
	v_mfma_f32_16x16x32_bf16 v[76:79], v[136:139], v[164:167], 0
	v_mfma_f32_16x16x32_bf16 v[124:127], v[128:131], v[184:187], 0
	v_mfma_f32_16x16x32_bf16 v[120:123], v[136:139], v[184:187], 0
	v_mfma_f32_16x16x32_bf16 v[116:119], v[128:131], v[192:195], 0
	v_mfma_f32_16x16x32_bf16 v[112:115], v[136:139], v[192:195], 0
	v_mfma_f32_16x16x32_bf16 v[108:111], v[128:131], v[200:203], 0
	v_mfma_f32_16x16x32_bf16 v[104:107], v[136:139], v[200:203], 0
	v_mfma_f32_16x16x32_bf16 v[84:87], v[132:135], v[180:183], v[84:87]
	v_mfma_f32_16x16x32_bf16 v[76:79], v[144:147], v[180:183], v[76:79]
	v_mfma_f32_16x16x32_bf16 v[124:127], v[132:135], v[188:191], v[124:127]
	v_mfma_f32_16x16x32_bf16 v[120:123], v[144:147], v[188:191], v[120:123]
	v_mfma_f32_16x16x32_bf16 v[116:119], v[132:135], v[196:199], v[116:119]
	v_mfma_f32_16x16x32_bf16 v[112:115], v[144:147], v[196:199], v[112:115]
	v_mfma_f32_16x16x32_bf16 v[108:111], v[132:135], v[204:207], v[108:111]
	v_mfma_f32_16x16x32_bf16 v[104:107], v[144:147], v[204:207], v[104:107]
	v_mfma_f32_16x16x32_bf16 v[60:63], v[148:151], v[164:167], 0
	v_mfma_f32_16x16x32_bf16 v[56:59], v[156:159], v[164:167], 0
	v_mfma_f32_16x16x32_bf16 v[52:55], v[148:151], v[184:187], 0
	v_mfma_f32_16x16x32_bf16 v[48:51], v[156:159], v[184:187], 0
	v_mfma_f32_16x16x32_bf16 v[44:47], v[148:151], v[192:195], 0
	v_mfma_f32_16x16x32_bf16 v[40:43], v[156:159], v[192:195], 0
	v_mfma_f32_16x16x32_bf16 v[36:39], v[148:151], v[200:203], 0
	v_mfma_f32_16x16x32_bf16 v[32:35], v[156:159], v[200:203], 0
	v_mfma_f32_16x16x32_bf16 v[60:63], v[152:155], v[180:183], v[60:63]
	v_mfma_f32_16x16x32_bf16 v[56:59], v[160:163], v[180:183], v[56:59]
	v_mfma_f32_16x16x32_bf16 v[52:55], v[152:155], v[188:191], v[52:55]
	v_mfma_f32_16x16x32_bf16 v[48:51], v[160:163], v[188:191], v[48:51]
	v_mfma_f32_16x16x32_bf16 v[44:47], v[152:155], v[196:199], v[44:47]
	v_mfma_f32_16x16x32_bf16 v[40:43], v[160:163], v[196:199], v[40:43]
	v_mfma_f32_16x16x32_bf16 v[36:39], v[152:155], v[204:207], v[36:39]
	v_mfma_f32_16x16x32_bf16 v[32:35], v[160:163], v[204:207], v[32:35]
	s_add_i32 s61, s61, 2
	s_add_u32 s22, s22, 0x100
	s_addc_u32 s23, s23, 0
	s_add_u32 s59, s59, 0x100
	s_addc_u32 s60, s60, 0
	s_barrier
	s_add_u32 s62, s38, 0x20000
	ds_read_b128 v[164:167], v177 offset:16384
	ds_read_b128 v[180:183], v177 offset:17408
	ds_read_b128 v[184:187], v177 offset:18432
	ds_read_b128 v[188:191], v177 offset:19456
	ds_read_b128 v[192:195], v177 offset:20480
	ds_read_b128 v[196:199], v177 offset:21504
	ds_read_b128 v[200:203], v177 offset:22528
	ds_read_b128 v[204:207], v177 offset:23552
	s_mov_b32 m0, s35
	s_nop 0
	global_load_lds_dwordx4 v171, s[38:39]
	s_mov_b32 m0, s36
	s_addc_u32 s63, s39, 0
	global_load_lds_dwordx4 v171, s[62:63]
	s_add_u32 s62, s38, 0x40000
	s_mov_b32 m0, s37
	s_addc_u32 s63, s39, 0
	global_load_lds_dwordx4 v171, s[62:63]
	s_add_u32 s62, s38, 0x60000
	s_mov_b32 m0, s40
	s_addc_u32 s63, s39, 0
	global_load_lds_dwordx4 v171, s[62:63]
	s_mov_b32 m0, s34
	s_nop 0
	global_load_lds_dwordx4 v170, s[24:25]
	s_add_u32 s62, s24, 0x20000
	s_mov_b32 m0, s41
	s_addc_u32 s63, s25, 0
	global_load_lds_dwordx4 v170, s[62:63]
	s_cmp_eq_u32 s17, 0
	s_cbranch_scc1 .Lpeel_strict_39287_0
	s_waitcnt vmcnt(24) lgkmcnt(0)
	s_branch .Lpeel_join_39287_0

; #define PG8_MMA(ai, bj, At, Bt) do { __builtin_amdgcn_s_setprio(1); _Pragma("unroll") for (int m = 0; m < 4; ++m) _Pragma("unroll") for (int n = 0; n < 2; ++n) _Pragma("unroll") for (int k = 0; k < 2; ++k) \
;         acc[ai][bj][m][n] = __builtin_amdgcn_mfma_f32_16x16x32_bf16(Bt[n][k], At[m][k], acc[ai][bj][m][n], 0, 0, 0); __builtin_amdgcn_s_setprio(0); } while (0)
; #define PG8_WAIT_V(n) asm volatile("s_waitcnt vmcnt(" #n ")" ::: "memory")
; #define PG8_WAIT_L(n) asm volatile("s_waitcnt lgkmcnt(" #n ")" ::: "memory")
; #define PG8_BAR __builtin_amdgcn_s_barrier()
; #define PG8_SCHED __builtin_amdgcn_sched_barrier(0)
; template <class Epi, class Sched>
; __device__ __forceinline__ void gemm_phase(LAS unsigned char* lds, const Sched& S, const Epi& E) {
;     ...
;             PG8_WAIT_V(8); PG8_WAIT_L(0); PG8_BAR; PG8_MMA(1, 0, At, B0); PG8_MMA(1, 1, At, B1); PG8_BAR; PG8_SCHED;
.Lpeel_join_39287_0:
	s_barrier
	v_mfma_f32_16x16x32_bf16 v[100:103], v[128:131], v[164:167], 0
	v_mfma_f32_16x16x32_bf16 v[96:99], v[136:139], v[164:167], 0
	v_mfma_f32_16x16x32_bf16 v[92:95], v[128:131], v[184:187], 0
	v_mfma_f32_16x16x32_bf16 v[88:91], v[136:139], v[184:187], 0
	v_mfma_f32_16x16x32_bf16 v[80:83], v[128:131], v[192:195], 0
	v_mfma_f32_16x16x32_bf16 v[72:75], v[136:139], v[192:195], 0
	v_mfma_f32_16x16x32_bf16 v[68:71], v[128:131], v[200:203], 0
	v_mfma_f32_16x16x32_bf16 v[64:67], v[136:139], v[200:203], 0
	v_mfma_f32_16x16x32_bf16 v[100:103], v[132:135], v[180:183], v[100:103]
	v_mfma_f32_16x16x32_bf16 v[96:99], v[144:147], v[180:183], v[96:99]
	v_mfma_f32_16x16x32_bf16 v[92:95], v[132:135], v[188:191], v[92:95]
	v_mfma_f32_16x16x32_bf16 v[88:91], v[144:147], v[188:191], v[88:91]
	v_mfma_f32_16x16x32_bf16 v[80:83], v[132:135], v[196:199], v[80:83]
	v_mfma_f32_16x16x32_bf16 v[72:75], v[144:147], v[196:199], v[72:75]
	v_mfma_f32_16x16x32_bf16 v[68:71], v[132:135], v[204:207], v[68:71]
	v_mfma_f32_16x16x32_bf16 v[64:67], v[144:147], v[204:207], v[64:67]
	v_mfma_f32_16x16x32_bf16 v[28:31], v[148:151], v[164:167], 0
	v_mfma_f32_16x16x32_bf16 v[24:27], v[156:159], v[164:167], 0
	v_mfma_f32_16x16x32_bf16 v[20:23], v[148:151], v[184:187], 0
	v_mfma_f32_16x16x32_bf16 v[16:19], v[156:159], v[184:187], 0
	v_mfma_f32_16x16x32_bf16 v[12:15], v[148:151], v[192:195], 0
	v_mfma_f32_16x16x32_bf16 v[8:11], v[156:159], v[192:195], 0
	v_mfma_f32_16x16x32_bf16 v[4:7], v[148:151], v[200:203], 0
	v_mfma_f32_16x16x32_bf16 v[0:3], v[156:159], v[200:203], 0
	v_mfma_f32_16x16x32_bf16 v[28:31], v[152:155], v[180:183], v[28:31]
	v_mfma_f32_16x16x32_bf16 v[24:27], v[160:163], v[180:183], v[24:27]
	v_mfma_f32_16x16x32_bf16 v[20:23], v[152:155], v[188:191], v[20:23]
	v_mfma_f32_16x16x32_bf16 v[16:19], v[160:163], v[188:191], v[16:19]
	v_mfma_f32_16x16x32_bf16 v[12:15], v[152:155], v[196:199], v[12:15]
	v_mfma_f32_16x16x32_bf16 v[8:11], v[160:163], v[196:199], v[8:11]
	v_mfma_f32_16x16x32_bf16 v[4:7], v[152:155], v[204:207], v[4:7]
	v_mfma_f32_16x16x32_bf16 v[0:3], v[160:163], v[204:207], v[0:3]
	s_barrier
	s_branch .Lpeel_mid_39287

; #define PG8_STAGE(bufoff, gbase, voff, p64) do { _Pragma("unroll") for (int _i = 0; _i < 2; ++_i) { \
;         const char* _gb = (const char*)(gbase) + (size_t)_i * (p64); const unsigned _la = ldsbase + (unsigned)(bufoff) + (unsigned)_i * 8192u; \
;         asm volatile("s_mov_b32 m0, %0\n\ts_nop 0\n\tglobal_load_lds_dwordx4 %1, %2" :: "s"(_la), "v"(voff), "s"(_gb) : "memory"); } } while (0)
; #define PG8_LDA(dst, b, h) do { _Pragma("unroll") for (int m = 0; m < 4; ++m) _Pragma("unroll") for (int k = 0; k < 2; ++k) dst[m][k] = *(const LAS bf16x8*)(lds + PG8_SA(b, h) + aoff + m * 2048 + k * 1024); } while (0)
; #define PG8_LDB(dst, b, h) do { _Pragma("unroll") for (int n = 0; n < 2; ++n) _Pragma("unroll") for (int k = 0; k < 2; ++k) dst[n][k] = *(const LAS bf16x8*)(lds + PG8_SB(b, h) + boff + n * 2048 + k * 1024); } while (0)
; #define PG8_MMA(ai, bj, At, Bt) do { __builtin_amdgcn_s_setprio(1); _Pragma("unroll") for (int m = 0; m < 4; ++m) _Pragma("unroll") for (int n = 0; n < 2; ++n) _Pragma("unroll") for (int k = 0; k < 2; ++k) \
;         acc[ai][bj][m][n] = __builtin_amdgcn_mfma_f32_16x16x32_bf16(Bt[n][k], At[m][k], acc[ai][bj][m][n], 0, 0, 0); __builtin_amdgcn_s_setprio(0); } while (0)
; #define PG8_WAIT_V(n) asm volatile("s_waitcnt vmcnt(" #n ")" ::: "memory")
; #define PG8_WAIT_L(n) asm volatile("s_waitcnt lgkmcnt(" #n ")" ::: "memory")
; #define PG8_BAR __builtin_amdgcn_s_barrier()
; #define PG8_SCHED __builtin_amdgcn_sched_barrier(0)
; template <class Epi, class Sched>
; __device__ __forceinline__ void gemm_phase(LAS unsigned char* lds, const Sched& S, const Epi& E) {
;     ...
;             PG8_LDB(B0, 0, 0); PG8_LDB(B1, 0, 1); PG8_SCHED; PG8_LDA(At, 0, 0); PG8_STAGE(PG8_SA(1, 1), a1 + hA, voffA, hA / 2);
;             PG8_WAIT_V(8); PG8_WAIT_L(0); PG8_BAR; PG8_MMA(0, 0, At, B0); PG8_MMA(0, 1, At, B1); PG8_BAR; PG8_SCHED;
.LBB0_1484:
	s_add_u32 s24, s24, 0x40080
	s_addc_u32 s25, s25, 0
	s_add_u32 s59, s26, 0x100
	s_addc_u32 s60, s27, 0
	s_mov_b32 s61, -2
	ds_read_b128 v[144:147], v138
	ds_read_b128 v[148:151], v138 offset:1024
	ds_read_b128 v[152:155], v138 offset:2048
	ds_read_b128 v[156:159], v138 offset:3072
	ds_read_b128 v[160:163], v139
	ds_read_b128 v[164:167], v139 offset:1024
	ds_read_b128 v[168:171], v139 offset:2048
	ds_read_b128 v[172:175], v139 offset:3072
	s_add_u32 s26, s24, 0xfffc0080
	s_addc_u32 s27, s25, -1
	s_cmp_eq_u32 s61, 12
	s_cselect_b32 s26, s20, s26
	s_cselect_b32 s27, s21, s27
	s_cselect_b32 s40, s22, s59
	s_cselect_b32 s41, s23, s60
	s_add_u32 s38, s26, 0x80
	s_addc_u32 s39, s27, 0
	ds_read_b128 v[178:181], v140
	ds_read_b128 v[182:185], v140 offset:1024
	ds_read_b128 v[186:189], v140 offset:2048
	ds_read_b128 v[190:193], v140 offset:3072
	ds_read_b128 v[194:197], v140 offset:4096
	ds_read_b128 v[198:201], v140 offset:5120
	ds_read_b128 v[202:205], v140 offset:6144
	ds_read_b128 v[206:209], v140 offset:7168
	s_mov_b32 m0, s54
	s_nop 0
	global_load_lds_dwordx4 v134, s[24:25]
	s_add_u32 s62, s24, 0x20000
	s_mov_b32 m0, s55
	s_addc_u32 s63, s25, 0
	global_load_lds_dwordx4 v134, s[62:63]
	s_cmp_eq_u32 s19, 0
	s_cbranch_scc1 .Lpeel_strict_42192_1
	s_waitcnt vmcnt(16) lgkmcnt(0)
	s_branch .Lpeel_join_42192_1

; #define PG8_STAGE(bufoff, gbase, voff, p64) do { _Pragma("unroll") for (int _i = 0; _i < 2; ++_i) { \
;         const char* _gb = (const char*)(gbase) + (size_t)_i * (p64); const unsigned _la = ldsbase + (unsigned)(bufoff) + (unsigned)_i * 8192u; \
;         asm volatile("s_mov_b32 m0, %0\n\ts_nop 0\n\tglobal_load_lds_dwordx4 %1, %2" :: "s"(_la), "v"(voff), "s"(_gb) : "memory"); } } while (0)
; #define PG8_LDA(dst, b, h) do { _Pragma("unroll") for (int m = 0; m < 4; ++m) _Pragma("unroll") for (int k = 0; k < 2; ++k) dst[m][k] = *(const LAS bf16x8*)(lds + PG8_SA(b, h) + aoff + m * 2048 + k * 1024); } while (0)
; #define PG8_MMA(ai, bj, At, Bt) do { __builtin_amdgcn_s_setprio(1); _Pragma("unroll") for (int m = 0; m < 4; ++m) _Pragma("unroll") for (int n = 0; n < 2; ++n) _Pragma("unroll") for (int k = 0; k < 2; ++k) \
;         acc[ai][bj][m][n] = __builtin_amdgcn_mfma_f32_16x16x32_bf16(Bt[n][k], At[m][k], acc[ai][bj][m][n], 0, 0, 0); __builtin_amdgcn_s_setprio(0); } while (0)
; #define PG8_WAIT_V(n) asm volatile("s_waitcnt vmcnt(" #n ")" ::: "memory")
; #define PG8_WAIT_L(n) asm volatile("s_waitcnt lgkmcnt(" #n ")" ::: "memory")
; #define PG8_BAR __builtin_amdgcn_s_barrier()
; #define PG8_SCHED __builtin_amdgcn_sched_barrier(0)
; template <class Epi, class Sched>
; __device__ __forceinline__ void gemm_phase(LAS unsigned char* lds, const Sched& S, const Epi& E) {
;     ...
;             PG8_WAIT_V(8); PG8_WAIT_L(0); PG8_BAR; PG8_MMA(0, 0, At, B0); PG8_MMA(0, 1, At, B1); PG8_BAR; PG8_SCHED;
;             PG8_LDA(At, 0, 1); PG8_STAGE(PG8_SB(0, 0), b2, vB2, hB2 / 2); PG8_STAGE(PG8_SB(0, 1), b2 + hB2, vB2, hB2 / 2); PG8_STAGE(PG8_SA(0, 0), a2, vA2, hA2 / 2);
.Lpeel_join_42192_1:
	s_barrier
	v_mfma_f32_16x16x32_bf16 v[124:127], v[144:147], v[178:181], 0
	v_mfma_f32_16x16x32_bf16 v[120:123], v[152:155], v[178:181], 0
	v_mfma_f32_16x16x32_bf16 v[108:111], v[144:147], v[186:189], 0
	v_mfma_f32_16x16x32_bf16 v[104:107], v[152:155], v[186:189], 0
	v_mfma_f32_16x16x32_bf16 v[92:95], v[144:147], v[194:197], 0
	v_mfma_f32_16x16x32_bf16 v[88:91], v[152:155], v[194:197], 0
	v_mfma_f32_16x16x32_bf16 v[76:79], v[144:147], v[202:205], 0
	v_mfma_f32_16x16x32_bf16 v[72:75], v[152:155], v[202:205], 0
	v_mfma_f32_16x16x32_bf16 v[124:127], v[148:151], v[182:185], v[124:127]
	v_mfma_f32_16x16x32_bf16 v[120:123], v[156:159], v[182:185], v[120:123]
	v_mfma_f32_16x16x32_bf16 v[108:111], v[148:151], v[190:193], v[108:111]
	v_mfma_f32_16x16x32_bf16 v[104:107], v[156:159], v[190:193], v[104:107]
	v_mfma_f32_16x16x32_bf16 v[92:95], v[148:151], v[198:201], v[92:95]
	v_mfma_f32_16x16x32_bf16 v[88:91], v[156:159], v[198:201], v[88:91]
	v_mfma_f32_16x16x32_bf16 v[76:79], v[148:151], v[206:209], v[76:79]
	v_mfma_f32_16x16x32_bf16 v[72:75], v[156:159], v[206:209], v[72:75]
	v_mfma_f32_16x16x32_bf16 v[116:119], v[160:163], v[178:181], 0
	v_mfma_f32_16x16x32_bf16 v[112:115], v[168:171], v[178:181], 0
	v_mfma_f32_16x16x32_bf16 v[100:103], v[160:163], v[186:189], 0
	v_mfma_f32_16x16x32_bf16 v[96:99], v[168:171], v[186:189], 0
	v_mfma_f32_16x16x32_bf16 v[84:87], v[160:163], v[194:197], 0
	v_mfma_f32_16x16x32_bf16 v[80:83], v[168:171], v[194:197], 0
	v_mfma_f32_16x16x32_bf16 v[68:71], v[160:163], v[202:205], 0
	v_mfma_f32_16x16x32_bf16 v[64:67], v[168:171], v[202:205], 0
	v_mfma_f32_16x16x32_bf16 v[116:119], v[164:167], v[182:185], v[116:119]
	v_mfma_f32_16x16x32_bf16 v[112:115], v[172:175], v[182:185], v[112:115]
	v_mfma_f32_16x16x32_bf16 v[100:103], v[164:167], v[190:193], v[100:103]
	v_mfma_f32_16x16x32_bf16 v[96:99], v[172:175], v[190:193], v[96:99]
	v_mfma_f32_16x16x32_bf16 v[84:87], v[164:167], v[198:201], v[84:87]
	v_mfma_f32_16x16x32_bf16 v[80:83], v[172:175], v[198:201], v[80:83]
	v_mfma_f32_16x16x32_bf16 v[68:71], v[164:167], v[206:209], v[68:71]
	v_mfma_f32_16x16x32_bf16 v[64:67], v[172:175], v[206:209], v[64:67]
	s_add_i32 s61, s61, 2
	s_add_u32 s24, s24, 0x100
	s_addc_u32 s25, s25, 0
	s_add_u32 s59, s59, 0x100
	s_addc_u32 s60, s60, 0
	s_barrier
	s_add_u32 s62, s40, 0x20000
	ds_read_b128 v[178:181], v140 offset:16384
	ds_read_b128 v[182:185], v140 offset:17408
	ds_read_b128 v[186:189], v140 offset:18432
	ds_read_b128 v[190:193], v140 offset:19456
	ds_read_b128 v[194:197], v140 offset:20480
	ds_read_b128 v[198:201], v140 offset:21504
	ds_read_b128 v[202:205], v140 offset:22528
	ds_read_b128 v[206:209], v140 offset:23552
	s_mov_b32 m0, s36
	s_nop 0
	global_load_lds_dwordx4 v135, s[40:41]
	s_mov_b32 m0, s37
	s_addc_u32 s63, s41, 0
	global_load_lds_dwordx4 v135, s[62:63]
	s_add_u32 s62, s40, 0x40000
	s_mov_b32 m0, s42
	s_addc_u32 s63, s41, 0
	global_load_lds_dwordx4 v135, s[62:63]
	s_add_u32 s62, s40, 0x60000
	s_mov_b32 m0, s43
	s_addc_u32 s63, s41, 0
	global_load_lds_dwordx4 v135, s[62:63]
	s_mov_b32 m0, s34
	s_nop 0
	global_load_lds_dwordx4 v134, s[26:27]
	s_add_u32 s62, s26, 0x20000
	s_mov_b32 m0, s44
	s_addc_u32 s63, s27, 0
	global_load_lds_dwordx4 v134, s[62:63]
	s_cmp_eq_u32 s19, 0
	s_cbranch_scc1 .Lpeel_strict_42192_0
	s_waitcnt vmcnt(16) lgkmcnt(0)
	s_branch .Lpeel_join_42192_0

; #define PG8_STAGE(bufoff, gbase, voff, p64) do { _Pragma("unroll") for (int _i = 0; _i < 2; ++_i) { \
;         const char* _gb = (const char*)(gbase) + (size_t)_i * (p64); const unsigned _la = ldsbase + (unsigned)(bufoff) + (unsigned)_i * 8192u; \
;         asm volatile("s_mov_b32 m0, %0\n\ts_nop 0\n\tglobal_load_lds_dwordx4 %1, %2" :: "s"(_la), "v"(voff), "s"(_gb) : "memory"); } } while (0)
; #define PG8_LDA(dst, b, h) do { _Pragma("unroll") for (int m = 0; m < 4; ++m) _Pragma("unroll") for (int k = 0; k < 2; ++k) dst[m][k] = *(const LAS bf16x8*)(lds + PG8_SA(b, h) + aoff + m * 2048 + k * 1024); } while (0)
; #define PG8_LDB(dst, b, h) do { _Pragma("unroll") for (int n = 0; n < 2; ++n) _Pragma("unroll") for (int k = 0; k < 2; ++k) dst[n][k] = *(const LAS bf16x8*)(lds + PG8_SB(b, h) + boff + n * 2048 + k * 1024); } while (0)
; #define PG8_MMA(ai, bj, At, Bt) do { __builtin_amdgcn_s_setprio(1); _Pragma("unroll") for (int m = 0; m < 4; ++m) _Pragma("unroll") for (int n = 0; n < 2; ++n) _Pragma("unroll") for (int k = 0; k < 2; ++k) \
;         acc[ai][bj][m][n] = __builtin_amdgcn_mfma_f32_16x16x32_bf16(Bt[n][k], At[m][k], acc[ai][bj][m][n], 0, 0, 0); __builtin_amdgcn_s_setprio(0); } while (0)
; #define PG8_WAIT_V(n) asm volatile("s_waitcnt vmcnt(" #n ")" ::: "memory")
; #define PG8_WAIT_L(n) asm volatile("s_waitcnt lgkmcnt(" #n ")" ::: "memory")
; #define PG8_BAR __builtin_amdgcn_s_barrier()
; #define PG8_SCHED __builtin_amdgcn_sched_barrier(0)
; template <class Epi, class Sched>
; __device__ __forceinline__ void gemm_phase(LAS unsigned char* lds, const Sched& S, const Epi& E) {
;     ...
;             PG8_LDB(B0, 0, 0); PG8_LDB(B1, 0, 1); PG8_SCHED; PG8_LDA(At, 0, 0); PG8_STAGE(PG8_SA(1, 1), a1 + hA, voffA, hA / 2);
;             PG8_WAIT_V(8); PG8_WAIT_L(0); PG8_BAR; PG8_MMA(0, 0, At, B0); PG8_MMA(0, 1, At, B1); PG8_BAR; PG8_SCHED;
.LBB0_1558:
	s_add_u32 s22, s22, 0xb0080
	s_addc_u32 s23, s23, 0
	s_add_u32 s59, s24, 0x100
	s_addc_u32 s60, s25, 0
	s_mov_b32 s61, -2
	s_waitcnt vmcnt(7)
	s_waitcnt vmcnt(6)
	s_waitcnt vmcnt(3)
	s_waitcnt vmcnt(2)
	s_waitcnt vmcnt(1)
	s_waitcnt vmcnt(0)
	ds_read_b128 v[128:131], v179
	ds_read_b128 v[132:135], v179 offset:1024
	ds_read_b128 v[136:139], v179 offset:2048
	ds_read_b128 v[140:143], v179 offset:3072
	ds_read_b128 v[150:153], v180
	ds_read_b128 v[154:157], v180 offset:1024
	ds_read_b128 v[158:161], v180 offset:2048
	ds_read_b128 v[162:165], v180 offset:3072
	s_add_u32 s24, s22, 0xfff50080
	s_addc_u32 s25, s23, -1
	s_cmp_eq_u32 s61, 40
	s_cselect_b32 s24, s18, s24
	s_cselect_b32 s25, s19, s25
	s_cselect_b32 s38, s20, s59
	s_cselect_b32 s39, s21, s60
	s_add_u32 s26, s24, 0x80
	s_addc_u32 s27, s25, 0
	ds_read_b128 v[166:169], v181
	ds_read_b128 v[170:173], v181 offset:1024
	ds_read_b128 v[184:187], v181 offset:2048
	ds_read_b128 v[188:191], v181 offset:3072
	ds_read_b128 v[192:195], v181 offset:4096
	ds_read_b128 v[196:199], v181 offset:5120
	ds_read_b128 v[200:203], v181 offset:6144
	ds_read_b128 v[204:207], v181 offset:7168
	s_mov_b32 m0, s54
	s_nop 0
	global_load_lds_dwordx4 v144, s[22:23]
	s_add_u32 s62, s22, 0x58000
	s_mov_b32 m0, s55
	s_addc_u32 s63, s23, 0
	global_load_lds_dwordx4 v144, s[62:63]
	s_cmp_eq_u32 s17, 0
	s_cbranch_scc1 .Lpeel_strict_43892_1
	s_waitcnt vmcnt(24) lgkmcnt(0)
	s_branch .Lpeel_join_43892_1

; #define PG8_STAGE(bufoff, gbase, voff, p64) do { _Pragma("unroll") for (int _i = 0; _i < 2; ++_i) { \
;         const char* _gb = (const char*)(gbase) + (size_t)_i * (p64); const unsigned _la = ldsbase + (unsigned)(bufoff) + (unsigned)_i * 8192u; \
;         asm volatile("s_mov_b32 m0, %0\n\ts_nop 0\n\tglobal_load_lds_dwordx4 %1, %2" :: "s"(_la), "v"(voff), "s"(_gb) : "memory"); } } while (0)
; #define PG8_LDA(dst, b, h) do { _Pragma("unroll") for (int m = 0; m < 4; ++m) _Pragma("unroll") for (int k = 0; k < 2; ++k) dst[m][k] = *(const LAS bf16x8*)(lds + PG8_SA(b, h) + aoff + m * 2048 + k * 1024); } while (0)
; #define PG8_MMA(ai, bj, At, Bt) do { __builtin_amdgcn_s_setprio(1); _Pragma("unroll") for (int m = 0; m < 4; ++m) _Pragma("unroll") for (int n = 0; n < 2; ++n) _Pragma("unroll") for (int k = 0; k < 2; ++k) \
;         acc[ai][bj][m][n] = __builtin_amdgcn_mfma_f32_16x16x32_bf16(Bt[n][k], At[m][k], acc[ai][bj][m][n], 0, 0, 0); __builtin_amdgcn_s_setprio(0); } while (0)
; #define PG8_WAIT_V(n) asm volatile("s_waitcnt vmcnt(" #n ")" ::: "memory")
; #define PG8_WAIT_L(n) asm volatile("s_waitcnt lgkmcnt(" #n ")" ::: "memory")
; #define PG8_BAR __builtin_amdgcn_s_barrier()
; #define PG8_SCHED __builtin_amdgcn_sched_barrier(0)
; template <class Epi, class Sched>
; __device__ __forceinline__ void gemm_phase(LAS unsigned char* lds, const Sched& S, const Epi& E) {
;     ...
;             PG8_WAIT_V(8); PG8_WAIT_L(0); PG8_BAR; PG8_MMA(0, 0, At, B0); PG8_MMA(0, 1, At, B1); PG8_BAR; PG8_SCHED;
;             PG8_LDA(At, 0, 1); PG8_STAGE(PG8_SB(0, 0), b2, vB2, hB2 / 2); PG8_STAGE(PG8_SB(0, 1), b2 + hB2, vB2, hB2 / 2); PG8_STAGE(PG8_SA(0, 0), a2, vA2, hA2 / 2);
.Lpeel_join_43892_1:
	s_barrier
	v_mfma_f32_16x16x32_bf16 v[124:127], v[128:131], v[166:169], 0
	v_mfma_f32_16x16x32_bf16 v[120:123], v[136:139], v[166:169], 0
	v_mfma_f32_16x16x32_bf16 v[116:119], v[128:131], v[184:187], 0
	v_mfma_f32_16x16x32_bf16 v[112:115], v[136:139], v[184:187], 0
	v_mfma_f32_16x16x32_bf16 v[108:111], v[128:131], v[192:195], 0
	v_mfma_f32_16x16x32_bf16 v[104:107], v[136:139], v[192:195], 0
	v_mfma_f32_16x16x32_bf16 v[100:103], v[128:131], v[200:203], 0
	v_mfma_f32_16x16x32_bf16 v[96:99], v[136:139], v[200:203], 0
	v_mfma_f32_16x16x32_bf16 v[124:127], v[132:135], v[170:173], v[124:127]
	v_mfma_f32_16x16x32_bf16 v[120:123], v[140:143], v[170:173], v[120:123]
	v_mfma_f32_16x16x32_bf16 v[116:119], v[132:135], v[188:191], v[116:119]
	v_mfma_f32_16x16x32_bf16 v[112:115], v[140:143], v[188:191], v[112:115]
	v_mfma_f32_16x16x32_bf16 v[108:111], v[132:135], v[196:199], v[108:111]
	v_mfma_f32_16x16x32_bf16 v[104:107], v[140:143], v[196:199], v[104:107]
	v_mfma_f32_16x16x32_bf16 v[100:103], v[132:135], v[204:207], v[100:103]
	v_mfma_f32_16x16x32_bf16 v[96:99], v[140:143], v[204:207], v[96:99]
	v_mfma_f32_16x16x32_bf16 v[60:63], v[150:153], v[166:169], 0
	v_mfma_f32_16x16x32_bf16 v[56:59], v[158:161], v[166:169], 0
	v_mfma_f32_16x16x32_bf16 v[52:55], v[150:153], v[184:187], 0
	v_mfma_f32_16x16x32_bf16 v[48:51], v[158:161], v[184:187], 0
	v_mfma_f32_16x16x32_bf16 v[44:47], v[150:153], v[192:195], 0
	v_mfma_f32_16x16x32_bf16 v[40:43], v[158:161], v[192:195], 0
	v_mfma_f32_16x16x32_bf16 v[36:39], v[150:153], v[200:203], 0
	v_mfma_f32_16x16x32_bf16 v[32:35], v[158:161], v[200:203], 0
	v_mfma_f32_16x16x32_bf16 v[60:63], v[154:157], v[170:173], v[60:63]
	v_mfma_f32_16x16x32_bf16 v[56:59], v[162:165], v[170:173], v[56:59]
	v_mfma_f32_16x16x32_bf16 v[52:55], v[154:157], v[188:191], v[52:55]
	v_mfma_f32_16x16x32_bf16 v[48:51], v[162:165], v[188:191], v[48:51]
	v_mfma_f32_16x16x32_bf16 v[44:47], v[154:157], v[196:199], v[44:47]
	v_mfma_f32_16x16x32_bf16 v[40:43], v[162:165], v[196:199], v[40:43]
	v_mfma_f32_16x16x32_bf16 v[36:39], v[154:157], v[204:207], v[36:39]
	v_mfma_f32_16x16x32_bf16 v[32:35], v[162:165], v[204:207], v[32:35]
	s_add_i32 s61, s61, 2
	s_add_u32 s22, s22, 0x100
	s_addc_u32 s23, s23, 0
	s_add_u32 s59, s59, 0x100
	s_addc_u32 s60, s60, 0
	s_barrier
	s_add_u32 s62, s38, 0x58000
	ds_read_b128 v[166:169], v181 offset:16384
	ds_read_b128 v[170:173], v181 offset:17408
	ds_read_b128 v[184:187], v181 offset:18432
	ds_read_b128 v[188:191], v181 offset:19456
	ds_read_b128 v[192:195], v181 offset:20480
	ds_read_b128 v[196:199], v181 offset:21504
	ds_read_b128 v[200:203], v181 offset:22528
	ds_read_b128 v[204:207], v181 offset:23552
	s_mov_b32 m0, s35
	s_nop 0
	global_load_lds_dwordx4 v145, s[38:39]
	s_mov_b32 m0, s36
	s_addc_u32 s63, s39, 0
	global_load_lds_dwordx4 v145, s[62:63]
	s_add_u32 s62, s38, 0xb0000
	s_mov_b32 m0, s37
	s_addc_u32 s63, s39, 0
	global_load_lds_dwordx4 v145, s[62:63]
	s_add_u32 s62, s38, 0x108000
	s_mov_b32 m0, s40
	s_addc_u32 s63, s39, 0
	global_load_lds_dwordx4 v145, s[62:63]
	s_mov_b32 m0, s34
	s_nop 0
	global_load_lds_dwordx4 v144, s[24:25]
	s_add_u32 s62, s24, 0x58000
	s_mov_b32 m0, s41
	s_addc_u32 s63, s25, 0
	global_load_lds_dwordx4 v144, s[62:63]
	s_cmp_eq_u32 s17, 0
	s_cbranch_scc1 .Lpeel_strict_43892_0
	s_waitcnt vmcnt(24) lgkmcnt(0)
	s_branch .Lpeel_join_43892_0

; #define PG8_MMA(ai, bj, At, Bt) do { __builtin_amdgcn_s_setprio(1); _Pragma("unroll") for (int m = 0; m < 4; ++m) _Pragma("unroll") for (int n = 0; n < 2; ++n) _Pragma("unroll") for (int k = 0; k < 2; ++k) \
;         acc[ai][bj][m][n] = __builtin_amdgcn_mfma_f32_16x16x32_bf16(Bt[n][k], At[m][k], acc[ai][bj][m][n], 0, 0, 0); __builtin_amdgcn_s_setprio(0); } while (0)
; #define PG8_WAIT_V(n) asm volatile("s_waitcnt vmcnt(" #n ")" ::: "memory")
; #define PG8_WAIT_L(n) asm volatile("s_waitcnt lgkmcnt(" #n ")" ::: "memory")
; #define PG8_BAR __builtin_amdgcn_s_barrier()
; #define PG8_SCHED __builtin_amdgcn_sched_barrier(0)
; template <class Epi, class Sched>
; __device__ __forceinline__ void gemm_phase(LAS unsigned char* lds, const Sched& S, const Epi& E) {
;     ...
;             PG8_WAIT_V(8); PG8_WAIT_L(0); PG8_BAR; PG8_MMA(1, 0, At, B0); PG8_MMA(1, 1, At, B1); PG8_BAR; PG8_SCHED;
.Lpeel_join_43892_0:
	s_barrier
	v_mfma_f32_16x16x32_bf16 v[92:95], v[128:131], v[166:169], 0
	v_mfma_f32_16x16x32_bf16 v[88:91], v[136:139], v[166:169], 0
	v_mfma_f32_16x16x32_bf16 v[84:87], v[128:131], v[184:187], 0
	v_mfma_f32_16x16x32_bf16 v[80:83], v[136:139], v[184:187], 0
	v_mfma_f32_16x16x32_bf16 v[76:79], v[128:131], v[192:195], 0
	v_mfma_f32_16x16x32_bf16 v[72:75], v[136:139], v[192:195], 0
	v_mfma_f32_16x16x32_bf16 v[68:71], v[128:131], v[200:203], 0
	v_mfma_f32_16x16x32_bf16 v[64:67], v[136:139], v[200:203], 0
	v_mfma_f32_16x16x32_bf16 v[92:95], v[132:135], v[170:173], v[92:95]
	v_mfma_f32_16x16x32_bf16 v[88:91], v[140:143], v[170:173], v[88:91]
	v_mfma_f32_16x16x32_bf16 v[84:87], v[132:135], v[188:191], v[84:87]
	v_mfma_f32_16x16x32_bf16 v[80:83], v[140:143], v[188:191], v[80:83]
	v_mfma_f32_16x16x32_bf16 v[76:79], v[132:135], v[196:199], v[76:79]
	v_mfma_f32_16x16x32_bf16 v[72:75], v[140:143], v[196:199], v[72:75]
	v_mfma_f32_16x16x32_bf16 v[68:71], v[132:135], v[204:207], v[68:71]
	v_mfma_f32_16x16x32_bf16 v[64:67], v[140:143], v[204:207], v[64:67]
	v_mfma_f32_16x16x32_bf16 v[28:31], v[150:153], v[166:169], 0
	v_mfma_f32_16x16x32_bf16 v[24:27], v[158:161], v[166:169], 0
	v_mfma_f32_16x16x32_bf16 v[20:23], v[150:153], v[184:187], 0
	v_mfma_f32_16x16x32_bf16 v[16:19], v[158:161], v[184:187], 0
	v_mfma_f32_16x16x32_bf16 v[12:15], v[150:153], v[192:195], 0
	v_mfma_f32_16x16x32_bf16 v[8:11], v[158:161], v[192:195], 0
	v_mfma_f32_16x16x32_bf16 v[4:7], v[150:153], v[200:203], 0
	v_mfma_f32_16x16x32_bf16 v[0:3], v[158:161], v[200:203], 0
	v_mfma_f32_16x16x32_bf16 v[28:31], v[154:157], v[170:173], v[28:31]
	v_mfma_f32_16x16x32_bf16 v[24:27], v[162:165], v[170:173], v[24:27]
	v_mfma_f32_16x16x32_bf16 v[20:23], v[154:157], v[188:191], v[20:23]
	v_mfma_f32_16x16x32_bf16 v[16:19], v[162:165], v[188:191], v[16:19]
	v_mfma_f32_16x16x32_bf16 v[12:15], v[154:157], v[196:199], v[12:15]
	v_mfma_f32_16x16x32_bf16 v[8:11], v[162:165], v[196:199], v[8:11]
	v_mfma_f32_16x16x32_bf16 v[4:7], v[154:157], v[204:207], v[4:7]
	v_mfma_f32_16x16x32_bf16 v[0:3], v[162:165], v[204:207], v[0:3]
	s_barrier
	s_branch .Lpeel_mid_43892
